# grid barriers: every workgroup (leaders too) waits on the cross-XCC arrival counter reaching its round target instead of a two-hop release; leader no longer waits for its release atomics
# speedup vs baseline: 1.0128x; 1.0026x over previous
; __device__ __forceinline__ unsigned xb_ld(unsigned* p)              { return __hip_atomic_load(p, __ATOMIC_RELAXED, __HIP_MEMORY_SCOPE_AGENT); }
; __device__ __forceinline__ unsigned xb_add(unsigned* p, unsigned v) { return __hip_atomic_fetch_add(p, v, __ATOMIC_RELAXED, __HIP_MEMORY_SCOPE_AGENT); }
; #define XB_SPIN(cond, bar) do { unsigned _sp = 0; while (cond) { __builtin_amdgcn_s_sleep(1); \
;     if ((++_sp & 255u) == 0u) { if (xb_ld(&(bar)[XB_TMO])) break; if (_sp > XB_SPIN_CAP) { atomicAdd(&(bar)[XB_TMO], 1u); break; } } } } while (0)
; __device__ __forceinline__ void xcd_barrier(const XcdBarrier& b) {
;     ...
;         const unsigned old = xb_add(&bar[XB_XSUB(b.x)], 1u);
;         const unsigned gen = old / nloc;
;         if (old + 1u == (gen + 1u) * nloc) {
;             __builtin_amdgcn_fence(__ATOMIC_RELEASE, "agent");
;             asm volatile("s_waitcnt vmcnt(0)" ::: "memory");
;             const unsigned og = xb_add(&bar[XB_TOP], 1u);
;             const unsigned tg = og / nx;
;             if (og + 1u == (tg + 1u) * nx) xb_add(&bar[XB_TOPGEN], 1u);
;             else XB_SPIN(xb_ld(&bar[XB_TOPGEN]) == tg, bar);
;             __builtin_amdgcn_fence(__ATOMIC_ACQUIRE, "agent");
;             xb_add(&bar[XB_XGEN(b.x)], 1u);
;             asm volatile("s_waitcnt vmcnt(0)" ::: "memory");
;         } else {
;             XB_SPIN(xb_ld(&bar[XB_XGEN(b.x)]) == gen, bar);
;             __builtin_amdgcn_fence(__ATOMIC_ACQUIRE, "agent");
.LBB0_123:
	s_or_b64 exec, exec, s[8:9]
	v_cvt_f32_u32_e32 v4, v2
	s_waitcnt vmcnt(0)
	v_readfirstlane_b32 s6, v3
	v_sub_u32_e32 v3, 0, v2
	v_rcp_iflag_f32_e32 v4, v4
	v_add_u32_e32 v5, s6, v1
	v_mul_f32_e32 v4, 0x4f7ffffe, v4
	v_cvt_u32_f32_e32 v4, v4
	v_mul_lo_u32 v1, v3, v4
	v_mul_hi_u32 v1, v4, v1
	v_add_u32_e32 v1, v4, v1
	v_mul_hi_u32 v1, v5, v1
	v_mul_lo_u32 v3, v1, v2
	v_sub_u32_e32 v3, v5, v3
	v_add_u32_e32 v4, 1, v1
	v_cmp_ge_u32_e32 vcc, v3, v2
	s_nop 1
	v_cndmask_b32_e32 v1, v1, v4, vcc
	v_sub_u32_e32 v4, v3, v2
	v_cndmask_b32_e32 v3, v3, v4, vcc
	v_add_u32_e32 v4, 1, v1
	v_cmp_ge_u32_e32 vcc, v3, v2
	v_add_u32_e32 v3, 1, v5
	s_nop 0
	v_cndmask_b32_e32 v1, v1, v4, vcc
	v_mul_lo_u32 v4, v2, v1
	v_add_u32_e32 v2, v4, v2
	v_cmp_ne_u32_e32 vcc, v3, v2
	s_and_saveexec_b64 s[6:7], vcc
	s_xor_b64 s[6:7], exec, s[6:7]
	s_cbranch_execz .LBB0_137
	s_waitcnt lgkmcnt(0)
	buffer_inv sc1
	v_mul_u32_u24_e32 v1, 1, v0
	v_mov_b32_e32 v0, 0
	s_add_u32 s12, s58, 0xc3400
	s_addc_u32 s13, s59, 0
	global_load_dword v0, v0, s[12:13] sc1
	s_waitcnt vmcnt(0)
	v_cmp_lt_u32_e32 vcc, v0, v1
	s_and_saveexec_b64 s[8:9], vcc
	s_cbranch_execz .LBB0_136
	s_add_u32 s10, s58, 0xc0200
	s_addc_u32 s11, s59, 0
	s_mov_b32 s24, 1
	s_mov_b64 s[14:15], 0
	v_mov_b32_e32 v0, 0
	s_branch .LBB0_127

; __device__ __forceinline__ unsigned xb_ld(unsigned* p)              { return __hip_atomic_load(p, __ATOMIC_RELAXED, __HIP_MEMORY_SCOPE_AGENT); }
; #define XB_SPIN(cond, bar) do { unsigned _sp = 0; while (cond) { __builtin_amdgcn_s_sleep(1); \
;     if ((++_sp & 255u) == 0u) { if (xb_ld(&(bar)[XB_TMO])) break; if (_sp > XB_SPIN_CAP) { atomicAdd(&(bar)[XB_TMO], 1u); break; } } } } while (0)
; __device__ __forceinline__ void xcd_barrier(const XcdBarrier& b) {
;     ...
;             XB_SPIN(xb_ld(&bar[XB_XGEN(b.x)]) == gen, bar);
.LBB0_131:
	global_load_dword v2, v0, s[12:13] sc1
	s_add_i32 s24, s24, 1
	s_mov_b64 s[20:21], -1
	s_waitcnt vmcnt(0)
	v_cmp_ge_u32_e32 vcc, v2, v1
	s_orn2_b64 s[18:19], vcc, exec
	s_branch .LBB0_126

; __device__ __forceinline__ unsigned xb_ld(unsigned* p)              { return __hip_atomic_load(p, __ATOMIC_RELAXED, __HIP_MEMORY_SCOPE_AGENT); }
; __device__ __forceinline__ unsigned xb_add(unsigned* p, unsigned v) { return __hip_atomic_fetch_add(p, v, __ATOMIC_RELAXED, __HIP_MEMORY_SCOPE_AGENT); }
; #define XB_SPIN(cond, bar) do { unsigned _sp = 0; while (cond) { __builtin_amdgcn_s_sleep(1); \
;     if ((++_sp & 255u) == 0u) { if (xb_ld(&(bar)[XB_TMO])) break; if (_sp > XB_SPIN_CAP) { atomicAdd(&(bar)[XB_TMO], 1u); break; } } } } while (0)
; __device__ __forceinline__ void xcd_barrier(const XcdBarrier& b) {
;     ...
;             const unsigned og = xb_add(&bar[XB_TOP], 1u);
;             const unsigned tg = og / nx;
;             if (og + 1u == (tg + 1u) * nx) xb_add(&bar[XB_TOPGEN], 1u);
;             else XB_SPIN(xb_ld(&bar[XB_TOPGEN]) == tg, bar);
.LBB0_140:
	s_or_b64 exec, exec, s[8:9]
	v_cvt_f32_u32_e32 v3, v0
	s_waitcnt vmcnt(0)
	v_readfirstlane_b32 s6, v2
	s_add_u32 s8, s58, 0xc3500
	s_addc_u32 s9, s59, 0
	v_rcp_iflag_f32_e32 v3, v3
	v_add_u32_e32 v1, s6, v1
	v_add_u32_e32 v4, 1, v1
	s_mov_b64 s[10:11], -1
	v_mul_f32_e32 v2, 0x4f7ffffe, v3
	v_cvt_u32_f32_e32 v2, v2
	v_sub_u32_e32 v3, 0, v0
	v_mul_lo_u32 v3, v3, v2
	v_mul_hi_u32 v3, v2, v3
	v_add_u32_e32 v2, v2, v3
	v_mul_hi_u32 v2, v1, v2
	v_mul_lo_u32 v3, v2, v0
	v_sub_u32_e32 v1, v1, v3
	v_add_u32_e32 v5, 1, v2
	v_cmp_ge_u32_e32 vcc, v1, v0
	v_sub_u32_e32 v3, v1, v0
	s_nop 0
	v_cndmask_b32_e32 v2, v2, v5, vcc
	v_cndmask_b32_e32 v1, v1, v3, vcc
	v_add_u32_e32 v3, 1, v2
	v_cmp_ge_u32_e32 vcc, v1, v0
	s_nop 1
	v_cndmask_b32_e32 v2, v2, v3, vcc
	v_mul_lo_u32 v1, v0, v2
	v_add_u32_e32 v0, v1, v0
	v_cmp_ne_u32_e32 vcc, v4, v0
	v_mov_b32_e32 v2, v0
	v_mov_b64_e32 v[0:1], s[8:9]
	s_and_saveexec_b64 s[6:7], vcc
	s_cbranch_execz .LBB0_152
	s_sub_u32 s8, s8, 0x100
	s_subb_u32 s9, s9, 0
	v_mov_b32_e32 v0, 0
	global_load_dword v1, v0, s[8:9] sc1
	s_mov_b64 s[14:15], 0
	s_waitcnt vmcnt(0)
	v_cmp_lt_u32_e32 vcc, v1, v2
	s_and_saveexec_b64 s[12:13], vcc
	s_cbranch_execz .LBB0_151
	s_add_u32 s10, s58, 0xc0200
	s_addc_u32 s11, s59, 0
	s_mov_b32 s24, 1
	s_branch .LBB0_144

; __device__ __forceinline__ unsigned xb_ld(unsigned* p)              { return __hip_atomic_load(p, __ATOMIC_RELAXED, __HIP_MEMORY_SCOPE_AGENT); }
; #define XB_SPIN(cond, bar) do { unsigned _sp = 0; while (cond) { __builtin_amdgcn_s_sleep(1); \
;     if ((++_sp & 255u) == 0u) { if (xb_ld(&(bar)[XB_TMO])) break; if (_sp > XB_SPIN_CAP) { atomicAdd(&(bar)[XB_TMO], 1u); break; } } } } while (0)
; __device__ __forceinline__ void xcd_barrier(const XcdBarrier& b) {
;     ...
;             else XB_SPIN(xb_ld(&bar[XB_TOPGEN]) == tg, bar);
.LBB0_148:
	global_load_dword v1, v0, s[8:9] sc1
	s_add_i32 s24, s24, 1
	s_mov_b64 s[18:19], -1
	s_waitcnt vmcnt(0)
	v_cmp_ge_u32_e32 vcc, v1, v2
	s_orn2_b64 s[22:23], vcc, exec
	s_branch .LBB0_143

; __device__ __forceinline__ unsigned cvt_pk(float lo, float hi) { unsigned r; asm volatile("v_cvt_pk_bf16_f32 %0, %1, %2" : "=v"(r) : "v"(lo), "v"(hi)); return r; }
; __device__ __forceinline__ float bf_lo(unsigned w) { return __uint_as_float(w << 16); }
; __device__ __forceinline__ float bf_hi(unsigned w) { return __uint_as_float(w & 0xffff0000u); }
; __device__ __forceinline__ void xcd_barrier(const XcdBarrier& b) {
;     ...
;             xb_add(&bar[XB_XGEN(b.x)], 1u);
;             asm volatile("s_waitcnt vmcnt(0)" ::: "memory");
;         } else {
;             XB_SPIN(xb_ld(&bar[XB_XGEN(b.x)]) == gen, bar);
;             __builtin_amdgcn_fence(__ATOMIC_ACQUIRE, "agent");
;             asm volatile("s_waitcnt vmcnt(0)" ::: "memory");
;         }
;     }
;     __syncthreads();
; }
; __device__ __forceinline__ void meta_proj(const Args& a, int wave, int lane) {
;     ...
;     for (int gw = blockIdx.x * NWAVES + wave; gw < 1536; gw += gridDim.x * NWAVES) {
;     const int n = 1024 + gw;
;     float wf[16];
;     { const u32x4 w0 = *(const u32x4*)(W1t + (size_t)n * DM + lane * 8), w1 = *(const u32x4*)(W1t + (size_t)n * DM + 512 + lane * 8);
;       const unsigned ww[8] = {w0.x, w0.y, w0.z, w0.w, w1.x, w1.y, w1.z, w1.w};
; #pragma unroll
;       for (int e = 0; e < 8; ++e) { wf[2 * e] = bf_lo(ww[e]); wf[2 * e + 1] = bf_hi(ww[e]); } }
;     float mine = 0.f;
; #pragma unroll
;     for (int r = 0; r < 16; ++r) {
;         const u32x4 x0 = *(const u32x4*)(XB + (size_t)(META_ROW + r) * DM + lane * 8), x1 = *(const u32x4*)(XB + (size_t)(META_ROW + r) * DM + 512 + lane * 8);
;         const unsigned xx[8] = {x0.x, x0.y, x0.z, x0.w, x1.x, x1.y, x1.z, x1.w};
;         float s = 0.f;
; #pragma unroll
;         for (int e = 0; e < 8; ++e) s += bf_lo(xx[e]) * wf[2 * e] + bf_hi(xx[e]) * wf[2 * e + 1];
;         s = wave_sum(s);
;         if (lane == r) mine = s;
;     }
;     if (lane < 16) {
;         const unsigned short o = (unsigned short)(cvt_pk(mine * rstdx[META_ROW + lane], 0.f) & 0xffffu);
;         const size_t row = META_ROW + lane;
;         if (n < 1280) ((bf16*)(ws + WS_K))[row * KVW + (n - 1024)] = o;
;         else if (n < 1536) ((bf16*)(ws + WS_V))[row * KVW + (n - 1280)] = o;
;         else ((bf16*)(ws + WS_U))[row * DM + (n - 1536)] = o;
.LBB0_156:
	s_or_b64 exec, exec, s[8:9]
.LBB0_157:
	s_or_b64 exec, exec, s[0:1]
	s_add_u32 s42, s58, 0x200000
	s_addc_u32 s43, s59, 0
	s_cmpk_gt_i32 s38, 0x5ff
	s_waitcnt lgkmcnt(0)
	s_barrier
	s_cbranch_scc1 .LBB0_169
	v_mbcnt_hi_u32_b32 v0, -1, v235
	v_and_b32_e32 v1, 64, v0
	v_add_u32_e32 v1, 64, v1
	v_xor_b32_e32 v2, 1, v0
	v_cmp_lt_i32_e32 vcc, v2, v1
	v_mov_b32_e32 v37, 0
	s_movk_i32 s4, 0x7fc
	v_cndmask_b32_e32 v2, v0, v2, vcc
	v_lshlrev_b32_e32 v113, 2, v2
	v_xor_b32_e32 v2, 2, v0
	v_cmp_lt_i32_e32 vcc, v2, v1
	s_mov_b32 s39, 0
	v_cmp_gt_u32_e64 s[0:1], 16, v128
	v_cndmask_b32_e32 v2, v0, v2, vcc
	v_lshlrev_b32_e32 v114, 2, v2
	v_xor_b32_e32 v2, 4, v0
	v_cmp_lt_i32_e32 vcc, v2, v1
	v_cmp_eq_u32_e64 s[6:7], 14, v128
	v_cmp_eq_u32_e64 s[8:9], 13, v128
	v_cndmask_b32_e32 v2, v0, v2, vcc
	v_lshlrev_b32_e32 v115, 2, v2
	v_xor_b32_e32 v2, 8, v0
	v_cmp_lt_i32_e32 vcc, v2, v1
	v_cmp_eq_u32_e64 s[10:11], 12, v128
	v_cmp_eq_u32_e64 s[12:13], 11, v128
	v_cndmask_b32_e32 v2, v0, v2, vcc
	v_lshlrev_b32_e32 v116, 2, v2
	v_xor_b32_e32 v2, 16, v0
	v_cmp_lt_i32_e32 vcc, v2, v1
	v_cmp_eq_u32_e64 s[14:15], 10, v128
	v_cmp_eq_u32_e64 s[16:17], 9, v128
	v_cndmask_b32_e32 v2, v0, v2, vcc
	v_lshlrev_b32_e32 v117, 2, v2
	v_xor_b32_e32 v2, 32, v0
	v_cmp_lt_i32_e32 vcc, v2, v1
	v_cmp_eq_u32_e64 s[18:19], 8, v128
	v_cmp_eq_u32_e64 s[20:21], 7, v128
	v_cndmask_b32_e32 v0, v0, v2, vcc
	v_lshlrev_b32_e32 v118, 2, v0
	v_or_b32_e32 v0, 0x8000, v128
	v_lshlrev_b32_e32 v36, 2, v0
	v_lshl_add_u64 v[38:39], s[58:59], 0, v[36:37]
	v_mad_u64_u32 v[40:41], s[4:5], v0, s4, v[38:39]
	v_lshlrev_b32_e32 v36, 9, v0
	v_mul_hi_i32_i24_e32 v1, 0xfffffa00, v0
	v_mul_i32_i24_e32 v0, 0xfffffa00, v0
	v_lshl_add_u64 v[42:43], v[40:41], 0, v[0:1]
	v_lshl_add_u64 v[0:1], s[58:59], 0, v[36:37]
	s_mov_b64 s[4:5], 0xaf00000
	v_lshlrev_b32_e32 v36, 4, v128
	v_lshl_add_u64 v[44:45], v[0:1], 0, s[4:5]
	v_lshl_add_u64 v[0:1], s[58:59], 0, v[36:37]
	s_mov_b64 s[4:5], 0x6c00000
	v_lshl_add_u64 v[46:47], v[0:1], 0, s[4:5]
	s_mov_b64 s[4:5], 0x6c00400
	v_lshl_add_u64 v[48:49], v[0:1], 0, s[4:5]
	s_mov_b64 s[4:5], 0x6c00800
	v_lshl_add_u64 v[50:51], v[0:1], 0, s[4:5]
	s_mov_b64 s[4:5], 0x6c00c00
	v_lshl_add_u64 v[52:53], v[0:1], 0, s[4:5]
	s_mov_b64 s[4:5], 0x6c01000
	v_lshl_add_u64 v[54:55], v[0:1], 0, s[4:5]
	s_mov_b64 s[4:5], 0x6c01400
	v_lshl_add_u64 v[56:57], v[0:1], 0, s[4:5]
	s_mov_b64 s[4:5], 0x6c01800
	v_lshl_add_u64 v[58:59], v[0:1], 0, s[4:5]
	s_mov_b64 s[4:5], 0x6c01c00
	v_lshl_add_u64 v[60:61], v[0:1], 0, s[4:5]
	s_mov_b64 s[4:5], 0x6c02000
	v_lshl_add_u64 v[62:63], v[0:1], 0, s[4:5]
	s_mov_b64 s[4:5], 0x6c02400
	v_lshl_add_u64 v[64:65], v[0:1], 0, s[4:5]
	s_mov_b64 s[4:5], 0x6c02800
	v_lshl_add_u64 v[66:67], v[0:1], 0, s[4:5]
	s_mov_b64 s[4:5], 0x6c02c00
	v_lshl_add_u64 v[68:69], v[0:1], 0, s[4:5]
	s_mov_b64 s[4:5], 0x6c03000
	v_lshl_add_u64 v[70:71], v[0:1], 0, s[4:5]
	s_mov_b64 s[4:5], 0x6c03400
	v_lshl_add_u64 v[72:73], v[0:1], 0, s[4:5]
	s_mov_b64 s[4:5], 0x6c03800
	v_lshl_add_u64 v[74:75], v[0:1], 0, s[4:5]
	s_mov_b64 s[4:5], 0x6c03c00
	v_lshl_add_u64 v[76:77], v[0:1], 0, s[4:5]
	s_mov_b64 s[4:5], 0x6c04000
	v_lshl_add_u64 v[78:79], v[0:1], 0, s[4:5]
	s_mov_b64 s[4:5], 0x6c04400
	v_lshl_add_u64 v[80:81], v[0:1], 0, s[4:5]
	s_mov_b64 s[4:5], 0x6c04800
	v_lshl_add_u64 v[82:83], v[0:1], 0, s[4:5]
	s_mov_b64 s[4:5], 0x6c04c00
	v_lshl_add_u64 v[84:85], v[0:1], 0, s[4:5]
	s_mov_b64 s[4:5], 0x6c05000
	v_lshl_add_u64 v[86:87], v[0:1], 0, s[4:5]
	s_mov_b64 s[4:5], 0x6c05400
	v_lshl_add_u64 v[88:89], v[0:1], 0, s[4:5]
	s_mov_b64 s[4:5], 0x6c05800
	v_lshl_add_u64 v[90:91], v[0:1], 0, s[4:5]
	s_mov_b64 s[4:5], 0x6c05c00
	v_lshl_add_u64 v[92:93], v[0:1], 0, s[4:5]
	s_mov_b64 s[4:5], 0x6c06000
	v_lshl_add_u64 v[94:95], v[0:1], 0, s[4:5]
	s_mov_b64 s[4:5], 0x6c06400
	v_lshl_add_u64 v[96:97], v[0:1], 0, s[4:5]
	s_mov_b64 s[4:5], 0x6c06800
	v_lshl_add_u64 v[98:99], v[0:1], 0, s[4:5]
	s_mov_b64 s[4:5], 0x6c06c00
	v_lshl_add_u64 v[100:101], v[0:1], 0, s[4:5]
	s_mov_b64 s[4:5], 0x6c07000
	v_lshl_add_u64 v[102:103], v[0:1], 0, s[4:5]
	s_mov_b64 s[4:5], 0x6c07400
	v_lshl_add_u64 v[104:105], v[0:1], 0, s[4:5]
	s_mov_b64 s[4:5], 0x6c07800
	v_lshl_add_u64 v[106:107], v[0:1], 0, s[4:5]
	s_mov_b64 s[4:5], 0x6c07c00
	v_lshl_add_u64 v[108:109], v[0:1], 0, s[4:5]
	v_cmp_eq_u32_e64 s[4:5], 15, v128
	v_cmp_eq_u32_e64 s[22:23], 6, v128
	v_cmp_eq_u32_e64 s[24:25], 5, v128
	v_cmp_eq_u32_e64 s[26:27], 4, v128
	v_cmp_eq_u32_e64 s[28:29], 3, v128
	v_cmp_eq_u32_e64 s[30:31], 2, v128
	v_cmp_eq_u32_e64 s[34:35], 1, v128
	v_cmp_eq_u32_e64 s[36:37], 0, v128
	v_lshl_add_u64 v[110:111], s[42:43], 0, v[36:37]
	s_branch .LBB0_160

; __device__ __forceinline__ unsigned xb_ld(unsigned* p)              { return __hip_atomic_load(p, __ATOMIC_RELAXED, __HIP_MEMORY_SCOPE_AGENT); }
; __device__ __forceinline__ unsigned xb_add(unsigned* p, unsigned v) { return __hip_atomic_fetch_add(p, v, __ATOMIC_RELAXED, __HIP_MEMORY_SCOPE_AGENT); }
; #define XB_SPIN(cond, bar) do { unsigned _sp = 0; while (cond) { __builtin_amdgcn_s_sleep(1); \
;     if ((++_sp & 255u) == 0u) { if (xb_ld(&(bar)[XB_TMO])) break; if (_sp > XB_SPIN_CAP) { atomicAdd(&(bar)[XB_TMO], 1u); break; } } } } while (0)
; __device__ __forceinline__ void xcd_barrier(const XcdBarrier& b) {
;     ...
;         const unsigned old = xb_add(&bar[XB_XSUB(b.x)], 1u);
;         const unsigned gen = old / nloc;
;         if (old + 1u == (gen + 1u) * nloc) {
;             __builtin_amdgcn_fence(__ATOMIC_RELEASE, "agent");
;             asm volatile("s_waitcnt vmcnt(0)" ::: "memory");
;             const unsigned og = xb_add(&bar[XB_TOP], 1u);
;             const unsigned tg = og / nx;
;             if (og + 1u == (tg + 1u) * nx) xb_add(&bar[XB_TOPGEN], 1u);
;             else XB_SPIN(xb_ld(&bar[XB_TOPGEN]) == tg, bar);
;             __builtin_amdgcn_fence(__ATOMIC_ACQUIRE, "agent");
;             xb_add(&bar[XB_XGEN(b.x)], 1u);
;             asm volatile("s_waitcnt vmcnt(0)" ::: "memory");
;         } else {
;             XB_SPIN(xb_ld(&bar[XB_XGEN(b.x)]) == gen, bar);
;             __builtin_amdgcn_fence(__ATOMIC_ACQUIRE, "agent");
.LBB0_211:
	s_or_b64 exec, exec, s[12:13]
	v_cvt_f32_u32_e32 v4, v2
	s_waitcnt vmcnt(0)
	v_readfirstlane_b32 s10, v3
	v_sub_u32_e32 v3, 0, v2
	v_rcp_iflag_f32_e32 v4, v4
	v_add_u32_e32 v5, s10, v1
	v_mul_f32_e32 v4, 0x4f7ffffe, v4
	v_cvt_u32_f32_e32 v4, v4
	v_mul_lo_u32 v1, v3, v4
	v_mul_hi_u32 v1, v4, v1
	v_add_u32_e32 v1, v4, v1
	v_mul_hi_u32 v1, v5, v1
	v_mul_lo_u32 v3, v1, v2
	v_sub_u32_e32 v3, v5, v3
	v_add_u32_e32 v4, 1, v1
	v_cmp_ge_u32_e32 vcc, v3, v2
	s_nop 1
	v_cndmask_b32_e32 v1, v1, v4, vcc
	v_sub_u32_e32 v4, v3, v2
	v_cndmask_b32_e32 v3, v3, v4, vcc
	v_add_u32_e32 v4, 1, v1
	v_cmp_ge_u32_e32 vcc, v3, v2
	v_add_u32_e32 v3, 1, v5
	s_nop 0
	v_cndmask_b32_e32 v1, v1, v4, vcc
	v_mul_lo_u32 v4, v2, v1
	v_add_u32_e32 v2, v4, v2
	v_cmp_ne_u32_e32 vcc, v3, v2
	s_and_saveexec_b64 s[10:11], vcc
	s_xor_b64 s[10:11], exec, s[10:11]
	s_cbranch_execz .LBB0_225
	s_waitcnt lgkmcnt(0)
	buffer_inv sc1
	v_mul_u32_u24_e32 v1, 2, v0
	v_mov_b32_e32 v0, 0
	s_add_u32 s16, s58, 0xc3400
	s_addc_u32 s17, s59, 0
	global_load_dword v0, v0, s[16:17] sc1
	s_waitcnt vmcnt(0)
	v_cmp_lt_u32_e32 vcc, v0, v1
	s_and_saveexec_b64 s[12:13], vcc
	s_cbranch_execz .LBB0_224
	s_add_u32 s14, s58, 0xc0200
	s_addc_u32 s15, s59, 0
	s_mov_b32 s28, 1
	s_mov_b64 s[18:19], 0
	v_mov_b32_e32 v0, 0
	s_branch .LBB0_215

; __device__ __forceinline__ unsigned xb_ld(unsigned* p)              { return __hip_atomic_load(p, __ATOMIC_RELAXED, __HIP_MEMORY_SCOPE_AGENT); }
; #define XB_SPIN(cond, bar) do { unsigned _sp = 0; while (cond) { __builtin_amdgcn_s_sleep(1); \
;     if ((++_sp & 255u) == 0u) { if (xb_ld(&(bar)[XB_TMO])) break; if (_sp > XB_SPIN_CAP) { atomicAdd(&(bar)[XB_TMO], 1u); break; } } } } while (0)
; __device__ __forceinline__ void xcd_barrier(const XcdBarrier& b) {
;     ...
;             XB_SPIN(xb_ld(&bar[XB_XGEN(b.x)]) == gen, bar);
.LBB0_219:
	global_load_dword v2, v0, s[16:17] sc1
	s_add_i32 s28, s28, 1
	s_mov_b64 s[24:25], -1
	s_waitcnt vmcnt(0)
	v_cmp_ge_u32_e32 vcc, v2, v1
	s_orn2_b64 s[22:23], vcc, exec
	s_branch .LBB0_214

; __device__ __forceinline__ unsigned xb_ld(unsigned* p)              { return __hip_atomic_load(p, __ATOMIC_RELAXED, __HIP_MEMORY_SCOPE_AGENT); }
; __device__ __forceinline__ unsigned xb_add(unsigned* p, unsigned v) { return __hip_atomic_fetch_add(p, v, __ATOMIC_RELAXED, __HIP_MEMORY_SCOPE_AGENT); }
; #define XB_SPIN(cond, bar) do { unsigned _sp = 0; while (cond) { __builtin_amdgcn_s_sleep(1); \
;     if ((++_sp & 255u) == 0u) { if (xb_ld(&(bar)[XB_TMO])) break; if (_sp > XB_SPIN_CAP) { atomicAdd(&(bar)[XB_TMO], 1u); break; } } } } while (0)
; __device__ __forceinline__ void xcd_barrier(const XcdBarrier& b) {
;     ...
;             const unsigned og = xb_add(&bar[XB_TOP], 1u);
;             const unsigned tg = og / nx;
;             if (og + 1u == (tg + 1u) * nx) xb_add(&bar[XB_TOPGEN], 1u);
;             else XB_SPIN(xb_ld(&bar[XB_TOPGEN]) == tg, bar);
.LBB0_228:
	s_or_b64 exec, exec, s[12:13]
	v_cvt_f32_u32_e32 v3, v0
	s_waitcnt vmcnt(0)
	v_readfirstlane_b32 s10, v2
	s_add_u32 s12, s58, 0xc3500
	s_addc_u32 s13, s59, 0
	v_rcp_iflag_f32_e32 v3, v3
	v_add_u32_e32 v1, s10, v1
	v_add_u32_e32 v4, 1, v1
	s_mov_b64 s[14:15], -1
	v_mul_f32_e32 v2, 0x4f7ffffe, v3
	v_cvt_u32_f32_e32 v2, v2
	v_sub_u32_e32 v3, 0, v0
	v_mul_lo_u32 v3, v3, v2
	v_mul_hi_u32 v3, v2, v3
	v_add_u32_e32 v2, v2, v3
	v_mul_hi_u32 v2, v1, v2
	v_mul_lo_u32 v3, v2, v0
	v_sub_u32_e32 v1, v1, v3
	v_add_u32_e32 v5, 1, v2
	v_cmp_ge_u32_e32 vcc, v1, v0
	v_sub_u32_e32 v3, v1, v0
	s_nop 0
	v_cndmask_b32_e32 v2, v2, v5, vcc
	v_cndmask_b32_e32 v1, v1, v3, vcc
	v_add_u32_e32 v3, 1, v2
	v_cmp_ge_u32_e32 vcc, v1, v0
	s_nop 1
	v_cndmask_b32_e32 v2, v2, v3, vcc
	v_mul_lo_u32 v1, v0, v2
	v_add_u32_e32 v0, v1, v0
	v_cmp_ne_u32_e32 vcc, v4, v0
	v_mov_b32_e32 v2, v0
	v_mov_b64_e32 v[0:1], s[12:13]
	s_and_saveexec_b64 s[10:11], vcc
	s_cbranch_execz .LBB0_240
	s_sub_u32 s12, s12, 0x100
	s_subb_u32 s13, s13, 0
	v_mov_b32_e32 v0, 0
	global_load_dword v1, v0, s[12:13] sc1
	s_mov_b64 s[18:19], 0
	s_waitcnt vmcnt(0)
	v_cmp_lt_u32_e32 vcc, v1, v2
	s_and_saveexec_b64 s[16:17], vcc
	s_cbranch_execz .LBB0_239
	s_add_u32 s14, s58, 0xc0200
	s_addc_u32 s15, s59, 0
	s_mov_b32 s28, 1
	s_branch .LBB0_232

; __device__ __forceinline__ unsigned xb_ld(unsigned* p)              { return __hip_atomic_load(p, __ATOMIC_RELAXED, __HIP_MEMORY_SCOPE_AGENT); }
; #define XB_SPIN(cond, bar) do { unsigned _sp = 0; while (cond) { __builtin_amdgcn_s_sleep(1); \
;     if ((++_sp & 255u) == 0u) { if (xb_ld(&(bar)[XB_TMO])) break; if (_sp > XB_SPIN_CAP) { atomicAdd(&(bar)[XB_TMO], 1u); break; } } } } while (0)
; __device__ __forceinline__ void xcd_barrier(const XcdBarrier& b) {
;     ...
;             else XB_SPIN(xb_ld(&bar[XB_TOPGEN]) == tg, bar);
.LBB0_236:
	global_load_dword v1, v0, s[12:13] sc1
	s_add_i32 s28, s28, 1
	s_mov_b64 s[22:23], -1
	s_waitcnt vmcnt(0)
	v_cmp_ge_u32_e32 vcc, v1, v2
	s_orn2_b64 s[26:27], vcc, exec
	s_branch .LBB0_231

; __device__ __forceinline__ void attn_item(const Args& a, LAS unsigned char* lds, int item, int wave, int lane) {
;     ...
;     const int r = wave >> 1, qh = wave & 1, hq = kvh * 4 + r, ql = lane & 31, hi = lane >> 5;
;     const float sink = a.in[6][hq];
;     const float* qnw = a.in[4];
;     const float L2E = 1.4426950408889634f;
;     for (int q4 = 0; q4 < 4; ++q4) {
;         const int bl = q4 >> 1, qb = q4 & 1, blk = blk0 + bl;
;         const int qblk = 2 * qh + qb;
;         const size_t qrow = (size_t)b * SEQ + blk * 128 + qblk * 32 + ql;
;         bf16x8 qf[4];
;         {
;             u32x4 qw[4]; float ss = 0.f;
; #pragma unroll
;             for (int ks = 0; ks < 4; ++ks) { qw[ks] = *(const u32x4*)(QB + qrow * DM + hq * 64 + 16 * ks + 8 * hi);
;                 const unsigned ww[4] = {qw[ks].x, qw[ks].y, qw[ks].z, qw[ks].w};
; #pragma unroll
;                 for (int e = 0; e < 4; ++e) { const float lo = bf_lo(ww[e]), h2 = bf_hi(ww[e]); ss += lo * lo + h2 * h2; } }
;             ss += __shfl_xor(ss, 32);
;             const float rs = __builtin_amdgcn_rsqf(ss * (1.0f / 64.0f) + EPS) * 0.125f;
; #pragma unroll
;             for (int ks = 0; ks < 4; ++ks) { const f32x4 g0 = *(const f32x4*)(qnw + 16 * ks + 8 * hi), g1 = *(const f32x4*)(qnw + 16 * ks + 8 * hi + 4);
;                 u32x4 o; o.x = cvt_pk(bf_lo(qw[ks].x) * rs * g0.x, bf_hi(qw[ks].x) * rs * g0.y); o.y = cvt_pk(bf_lo(qw[ks].y) * rs * g0.z, bf_hi(qw[ks].y) * rs * g0.w);
;                 o.z = cvt_pk(bf_lo(qw[ks].z) * rs * g1.x, bf_hi(qw[ks].z) * rs * g1.y); o.w = cvt_pk(bf_lo(qw[ks].w) * rs * g1.z, bf_hi(qw[ks].w) * rs * g1.w);
;                 qf[ks] = __builtin_bit_cast(bf16x8, o); }
;         }
;         f32x16 S[6];
; #pragma unroll
;         for (int i = 0; i < 6; ++i) {
;             const int kb = (i == 0) ? 0 : 4 * bl + qblk + i;
;             f32x16 acc;
; #pragma unroll
;             for (int e = 0; e < 16; ++e) acc[e] = 0.f;
; #pragma unroll
; __device__ __forceinline__ void xcd_barrier(const XcdBarrier& b) {
;     ...
;             xb_add(&bar[XB_XGEN(b.x)], 1u);
;             asm volatile("s_waitcnt vmcnt(0)" ::: "memory");
;         } else {
;             XB_SPIN(xb_ld(&bar[XB_XGEN(b.x)]) == gen, bar);
;             __builtin_amdgcn_fence(__ATOMIC_ACQUIRE, "agent");
;             asm volatile("s_waitcnt vmcnt(0)" ::: "memory");
;         }
;     }
;     __syncthreads();
; }
.LBB0_244:
	s_or_b64 exec, exec, s[12:13]
.LBB0_245:
	s_or_b64 exec, exec, s[0:1]
	s_add_u32 s60, s58, 0x60000
	s_addc_u32 s61, s59, 0
	s_cmpk_lt_i32 s2, 0x200
	s_cselect_b64 s[54:55], -1, 0
	s_cmpk_gt_i32 s2, 0x1ff
	v_lshrrev_b32_e32 v105, 5, v128
	v_cmp_gt_u32_e64 s[0:1], 32, v128
	v_or_b32_e32 v104, 32, v128
	s_waitcnt lgkmcnt(0)
	s_barrier
	s_cbranch_scc1 .LBB0_261
	v_mbcnt_hi_u32_b32 v2, -1, v235
	v_and_b32_e32 v1, 64, v2
	v_xor_b32_e32 v0, 1, v2
	v_add_u32_e32 v3, 64, v1
	v_cmp_lt_i32_e32 vcc, v0, v3
	v_mov_b32_e32 v99, 0
	v_mov_b32_e32 v1, v99
	v_cndmask_b32_e32 v0, v2, v0, vcc
	v_lshlrev_b32_e32 v113, 2, v0
	v_xor_b32_e32 v0, 2, v2
	v_cmp_lt_i32_e32 vcc, v0, v3
	v_lshlrev_b32_e32 v96, 4, v131
	v_mov_b32_e32 v97, v99
	v_cndmask_b32_e32 v0, v2, v0, vcc
	v_lshlrev_b32_e32 v124, 2, v0
	v_xor_b32_e32 v0, 4, v2
	v_cmp_lt_i32_e32 vcc, v0, v3
	v_lshlrev_b32_e32 v98, 5, v131
	v_lshl_add_u64 v[100:101], s[4:5], 0, v[96:97]
	v_cndmask_b32_e32 v0, v2, v0, vcc
	v_lshlrev_b32_e32 v125, 2, v0
	v_lshlrev_b32_e32 v0, 4, v105
	v_lshl_add_u64 v[108:109], s[48:49], 0, v[0:1]
	v_xor_b32_e32 v1, 32, v2
	v_cmp_lt_i32_e32 vcc, v1, v3
	v_lshl_add_u64 v[106:107], s[86:87], 0, v[98:99]
	s_lshl_b32 s4, s33, 1
	v_lshlrev_b32_e32 v98, 3, v105
	v_cndmask_b32_e32 v1, v2, v1, vcc
	v_and_b32_e32 v2, 32, v128
	v_mov_b32_e32 v3, v99
	v_lshl_add_u64 v[102:103], s[6:7], 0, v[96:97]
	s_and_b32 s65, s4, 2
	v_lshlrev_b32_e32 v97, 2, v1
	v_lshl_add_u64 v[110:111], s[84:85], 0, v[2:3]
	v_add_u32_e32 v112, 0, v0
	v_lshlrev_b32_e32 v2, 2, v105
	v_lshl_add_u64 v[0:1], s[58:59], 0, v[98:99]
	s_mov_b64 s[4:5], 0x19400000
	v_lshl_add_u64 v[114:115], v[0:1], 0, s[4:5]
	v_or_b32_e32 v1, 2, v2
	v_cmp_gt_u32_e64 s[8:9], v1, v130
	v_or_b32_e32 v1, 3, v2
	v_cmp_gt_u32_e64 s[10:11], v1, v130
	v_or_b32_e32 v1, 8, v2
	v_cmp_gt_u32_e64 s[12:13], v1, v130
	v_or_b32_e32 v1, 9, v2
	v_cmp_gt_u32_e64 s[14:15], v1, v130
	v_or_b32_e32 v1, 10, v2
	v_cmp_gt_u32_e64 s[16:17], v1, v130
	v_or_b32_e32 v1, 11, v2
	v_cmp_gt_u32_e64 s[18:19], v1, v130
	v_or_b32_e32 v1, 16, v2
	v_cmp_gt_u32_e64 s[20:21], v1, v130
	v_or_b32_e32 v1, 17, v2
	v_cmp_gt_u32_e64 s[22:23], v1, v130
	v_or_b32_e32 v1, 18, v2
	v_cmp_gt_u32_e64 s[24:25], v1, v130
	v_or_b32_e32 v1, 19, v2
	v_cmp_gt_u32_e64 s[26:27], v1, v130
	v_or_b32_e32 v1, 24, v2
	v_cmp_gt_u32_e64 s[28:29], v1, v130
	v_or_b32_e32 v1, 25, v2
	v_cmp_gt_u32_e64 s[30:31], v1, v130
	v_or_b32_e32 v1, 26, v2
	s_lshr_b32 s41, s41, 7
	v_cmp_gt_u32_e64 s[34:35], v1, v130
	v_or_b32_e32 v1, 27, v2
	v_mul_u32_u24_e32 v4, 0x1a30, v131
	v_sub_u32_e32 v3, v112, v98
	s_movk_i32 s76, 0x90
	v_mul_u32_u24_e32 v0, 0x90, v130
	v_cmp_gt_u32_e64 s[36:37], v1, v130
	s_cmp_eq_u32 s65, 0
	s_movk_i32 s42, 0x348
	v_lshlrev_b32_e32 v1, 1, v141
	s_mov_b32 s63, 0
	v_cmp_gt_u32_e64 s[4:5], v2, v130
	v_cmp_lt_u32_e64 s[6:7], v2, v130
	s_cselect_b64 s[38:39], -1, 0
	v_mad_u32_u24 v126, v130, s42, v3
	v_mad_u32_u24 v127, v104, s42, v3
	v_or_b32_e32 v132, 0x8000, v141
	v_add3_u32 v133, v4, v1, 0
	v_mad_u32_u24 v134, v141, s76, 0
	s_lshl_b32 s77, s2, 1
	s_lshl_b32 s78, s92, 1
	s_movk_i32 s79, 0x7f
	s_movk_i32 s80, 0x100
	s_movk_i32 s81, 0x500
	v_mov_b32_e32 v135, 0x358637bd
	s_movk_i32 s82, 0xaff
	s_mov_b32 s64, 0x3fb8aa3b
	v_add_u32_e32 v136, v112, v0
	s_mov_b32 s83, 0xff800000
	v_mov_b32_e32 v137, 0xff800000
	s_mov_b32 s84, s2
	s_branch .LBB0_248

; __device__ __forceinline__ unsigned xb_ld(unsigned* p)              { return __hip_atomic_load(p, __ATOMIC_RELAXED, __HIP_MEMORY_SCOPE_AGENT); }
; __device__ __forceinline__ unsigned xb_add(unsigned* p, unsigned v) { return __hip_atomic_fetch_add(p, v, __ATOMIC_RELAXED, __HIP_MEMORY_SCOPE_AGENT); }
; #define XB_SPIN(cond, bar) do { unsigned _sp = 0; while (cond) { __builtin_amdgcn_s_sleep(1); \
;     if ((++_sp & 255u) == 0u) { if (xb_ld(&(bar)[XB_TMO])) break; if (_sp > XB_SPIN_CAP) { atomicAdd(&(bar)[XB_TMO], 1u); break; } } } } while (0)
; __device__ __forceinline__ void xcd_barrier(const XcdBarrier& b) {
;     ...
;         const unsigned old = xb_add(&bar[XB_XSUB(b.x)], 1u);
;         const unsigned gen = old / nloc;
;         if (old + 1u == (gen + 1u) * nloc) {
;             __builtin_amdgcn_fence(__ATOMIC_RELEASE, "agent");
;             asm volatile("s_waitcnt vmcnt(0)" ::: "memory");
;             const unsigned og = xb_add(&bar[XB_TOP], 1u);
;             const unsigned tg = og / nx;
;             if (og + 1u == (tg + 1u) * nx) xb_add(&bar[XB_TOPGEN], 1u);
;             else XB_SPIN(xb_ld(&bar[XB_TOPGEN]) == tg, bar);
;             __builtin_amdgcn_fence(__ATOMIC_ACQUIRE, "agent");
;             xb_add(&bar[XB_XGEN(b.x)], 1u);
;             asm volatile("s_waitcnt vmcnt(0)" ::: "memory");
;         } else {
;             XB_SPIN(xb_ld(&bar[XB_XGEN(b.x)]) == gen, bar);
;             __builtin_amdgcn_fence(__ATOMIC_ACQUIRE, "agent");
.LBB0_292:
	s_or_b64 exec, exec, s[8:9]
	v_cvt_f32_u32_e32 v4, v2
	s_waitcnt vmcnt(0)
	v_readfirstlane_b32 s6, v3
	v_sub_u32_e32 v3, 0, v2
	v_rcp_iflag_f32_e32 v4, v4
	v_add_u32_e32 v5, s6, v1
	v_mul_f32_e32 v4, 0x4f7ffffe, v4
	v_cvt_u32_f32_e32 v4, v4
	v_mul_lo_u32 v1, v3, v4
	v_mul_hi_u32 v1, v4, v1
	v_add_u32_e32 v1, v4, v1
	v_mul_hi_u32 v1, v5, v1
	v_mul_lo_u32 v3, v1, v2
	v_sub_u32_e32 v3, v5, v3
	v_add_u32_e32 v4, 1, v1
	v_cmp_ge_u32_e32 vcc, v3, v2
	s_nop 1
	v_cndmask_b32_e32 v1, v1, v4, vcc
	v_sub_u32_e32 v4, v3, v2
	v_cndmask_b32_e32 v3, v3, v4, vcc
	v_add_u32_e32 v4, 1, v1
	v_cmp_ge_u32_e32 vcc, v3, v2
	v_add_u32_e32 v3, 1, v5
	s_nop 0
	v_cndmask_b32_e32 v1, v1, v4, vcc
	v_mul_lo_u32 v4, v2, v1
	v_add_u32_e32 v2, v4, v2
	v_cmp_ne_u32_e32 vcc, v3, v2
	s_and_saveexec_b64 s[6:7], vcc
	s_xor_b64 s[6:7], exec, s[6:7]
	s_cbranch_execz .LBB0_306
	s_waitcnt lgkmcnt(0)
	buffer_inv sc1
	v_mul_u32_u24_e32 v1, 3, v0
	v_mov_b32_e32 v0, 0
	s_add_u32 s12, s58, 0xc3400
	s_addc_u32 s13, s59, 0
	global_load_dword v0, v0, s[12:13] sc1
	s_waitcnt vmcnt(0)
	v_cmp_lt_u32_e32 vcc, v0, v1
	s_and_saveexec_b64 s[8:9], vcc
	s_cbranch_execz .LBB0_305
	s_add_u32 s10, s58, 0xc0200
	s_addc_u32 s11, s59, 0
	s_mov_b32 s24, 1
	s_mov_b64 s[14:15], 0
	v_mov_b32_e32 v0, 0
	s_branch .LBB0_296

; template <bool FINAL>
; __device__ __forceinline__ void ssm_item(const Args& a, LAS unsigned char* lds, int item, int wave, int lane) {
;     ...
;     const bf16* U = (const bf16*)(ws + WS_U); bf16* Z = (bf16*)(ws + WS_Q);
;     float* E = (float*)(ws + WS_E);
;     const bool meta = (!FINAL) && item >= 256;
;     const int oct = item & 7, cp = (item >> 3) & 15, bp = (item >> 7) & 1;
;     const int g = oct * 8 + wave, j = lane & 31, hi = lane >> 5;
;     const int b0 = bp * 2, c0 = 2 * cp;
;     bf16x8 bbf[4];
; #pragma unroll
;     for (int k = 0; k < 4; ++k) bbf[k] = *(const bf16x8*)((const bf16*)(ws + WS_BB) + ((size_t)g * 128 + k * 32 + j) * 16 + 8 * hi);
;     const f32x2 a0 = ((const f32x2*)(ws + WS_ATAB))[g * 64 + j], a1 = ((const f32x2*)(ws + WS_ATAB))[g * 64 + 32 + j];
;     const f32x2 a0x = (f32x2){a0.x, a0.x}, a0y = (f32x2){a0.y, a0.y}, na0y = (f32x2){-a0.y, -a0.y}, a1x = (f32x2){a1.x, a1.x}, a1y = (f32x2){a1.y, a1.y}, na1y = (f32x2){-a1.y, -a1.y};
;     f32x2 s0r = (f32x2){0.f, 0.f}, s0i = s0r, s1r = s0r, s1i = s0r;
;     bf16x8 cmf[4]; f32x4 dsk;
;     if (FINAL) {
; #pragma unroll
;         for (int k = 0; k < 4; ++k) cmf[k] = *(const bf16x8*)((const bf16*)(ws + WS_CM) + ((size_t)g * 16 + (lane & 15)) * 128 + 32 * k + 8 * (lane >> 4));
;         dsk = *(const f32x4*)(a.in[14] + g * 16 + 4 * (lane >> 4));
;         const f32x2 t0 = ((const f32x2*)(ws + WS_ATAB2))[g * 64 + j], t1 = ((const f32x2*)(ws + WS_ATAB2))[g * 64 + 32 + j];
;         const f32x2 m0 = ((const f32x2*)(ws + WS_SMETA))[g * 64 + j], m1 = ((const f32x2*)(ws + WS_SMETA))[g * 64 + 32 + j];
;         float c0r = m0.x, c0i = m0.y, c1r = m1.x, c1i = m1.y;
;         const f32x2* Eb = (const f32x2*)E + ((size_t)((b0 + hi) * 64 + g) * NCHUNK) * 64;
; #pragma unroll
;         for (int half = 0; half < 2; ++half) {
;             if (half * 16 < c0) {
;                 f32x2 e0[16], e1[16];
; #pragma unroll
; __device__ __forceinline__ void xcd_barrier(const XcdBarrier& b) {
;     ...
;             xb_add(&bar[XB_XGEN(b.x)], 1u);
;             asm volatile("s_waitcnt vmcnt(0)" ::: "memory");
;         } else {
;             XB_SPIN(xb_ld(&bar[XB_XGEN(b.x)]) == gen, bar);
;             __builtin_amdgcn_fence(__ATOMIC_ACQUIRE, "agent");
;             asm volatile("s_waitcnt vmcnt(0)" ::: "memory");
;         }
;     }
;     __syncthreads();
; }
.LBB0_325:
	s_or_b64 exec, exec, s[8:9]
.LBB0_326:
	s_or_b64 exec, exec, s[0:1]
	s_cmpk_gt_i32 s2, 0xff
	v_lshlrev_b32_e32 v238, 8, v224
	s_waitcnt lgkmcnt(0)
	s_barrier
	s_cbranch_scc1 .LBB0_341
	v_mov_b32_e32 v107, 0
	v_lshlrev_b32_e32 v106, 4, v105
	v_lshl_add_u64 v[2:3], s[58:59], 0, v[106:107]
	v_lshlrev_b32_e32 v106, 5, v130
	v_lshl_add_u64 v[2:3], v[2:3], 0, v[106:107]
	s_mov_b64 s[0:1], 0x100000
	v_and_b32_e32 v106, 0xf00, v238
	v_lshl_add_u64 v[108:109], v[2:3], 0, s[0:1]
	s_add_u32 s0, s58, 0x80000
	v_lshl_add_u64 v[2:3], s[58:59], 0, v[106:107]
	v_and_b32_e32 v106, 48, v128
	s_addc_u32 s1, s59, 0
	v_lshl_add_u64 v[2:3], v[2:3], 0, v[106:107]
	s_mov_b64 s[4:5], 0x140000
	v_lshl_add_u64 v[110:111], v[2:3], 0, s[4:5]
	s_add_u32 s4, s58, 0x2200000
	s_addc_u32 s5, s59, 0
	s_add_u32 s6, s58, 0x88000
	s_addc_u32 s7, s59, 0
	v_and_b32_e32 v2, 12, v116
	s_add_u32 s8, s58, 0x90000
	s_mul_i32 s10, s33, 0x2200
	v_lshlrev_b32_e32 v106, 2, v2
	s_addc_u32 s9, s59, 0
	s_add_i32 s10, s10, 0
	v_lshl_add_u64 v[112:113], s[72:73], 0, v[106:107]
	v_mov_b32_e32 v7, 0x80
	v_and_b32_e32 v9, 48, v224
	s_movk_i32 s12, 0x1100
	v_mov_b32_e32 v11, s10
	v_and_b32_e32 v106, 16, v129
	v_lshlrev_b32_e32 v15, 8, v165
	v_lshlrev_b32_e32 v0, 3, v105
	v_or_b32_e32 v4, 0x60, v128
	v_or_b32_e32 v6, 0xe0, v128
	v_or_b32_e32 v8, 0x120, v128
	v_or_b32_e32 v10, 0x160, v128
	v_or_b32_e32 v12, 0x1a0, v128
	v_or_b32_e32 v14, 0x1e0, v128
	v_or_b32_e32 v16, 0x220, v128
	v_or_b32_e32 v18, 0x260, v128
	v_or_b32_e32 v20, 0x2a0, v128
	v_or_b32_e32 v22, 0x2e0, v128
	v_or_b32_e32 v24, 0x320, v128
	v_or_b32_e32 v26, 0x360, v128
	v_or_b32_e32 v28, 0x3a0, v128
	v_or_b32_e32 v30, 0x3e0, v224
	v_or_b32_e32 v32, 0xa0, v128
	v_or_b32_e32 v34, 0x460, v128
	v_or_b32_e32 v36, 0x4e0, v128
	v_or_b32_e32 v38, 0x520, v128
	v_or_b32_e32 v40, 0x560, v128
	v_or_b32_e32 v42, 0x5a0, v128
	v_or_b32_e32 v44, 0x5e0, v128
	v_or_b32_e32 v46, 0x620, v128
	v_or_b32_e32 v48, 0x660, v128
	v_or_b32_e32 v50, 0x6a0, v128
	v_or_b32_e32 v52, 0x6e0, v128
	v_or_b32_e32 v54, 0x720, v128
	v_or_b32_e32 v56, 0x760, v128
	v_or_b32_e32 v58, 0x420, v128
	v_or_b32_e32 v60, 0x4a0, v128
	v_bfe_u32 v1, v128, 1, 1
	v_and_b32_e32 v3, 6, v116
	v_lshrrev_b32_e32 v169, 3, v227
	v_lshlrev_b32_e32 v5, 2, v130
	v_lshl_or_b32 v7, v128, 2, v7
	v_add_u32_e32 v9, s10, v9
	v_mad_u32_u24 v11, v105, s12, v11
	v_mul_u32_u24_e32 v13, 0x110, v227
	v_mov_b32_e32 v161, v107
	v_lshl_add_u64 v[62:63], s[58:59], 0, v[106:107]
	s_mov_b64 s[12:13], 0xd104000
	v_lshl_or_b32 v15, v163, 13, v15
	v_or_b32_e32 v167, v1, v3
	s_mov_b32 s11, 0
	v_lshl_add_u64 v[114:115], s[58:59], 0, v[160:161]
	v_lshl_or_b32 v161, v169, 8, v131
	s_lshl_b32 s14, s33, 4
	v_lshl_add_u64 v[116:117], v[62:63], 0, s[12:13]
	v_or3_b32 v241, v15, v3, v1
	v_lshlrev_b32_e32 v118, 3, v4
	v_lshlrev_b32_e32 v120, 3, v6
	v_lshlrev_b32_e32 v122, 3, v8
	v_lshlrev_b32_e32 v124, 3, v10
	v_lshlrev_b32_e32 v126, 3, v12
	v_lshlrev_b32_e32 v128, 3, v14
	s_movk_i32 s15, 0x1000
	v_lshlrev_b32_e32 v132, 3, v16
	v_lshlrev_b32_e32 v134, 3, v18
	v_lshlrev_b32_e32 v136, 3, v20
	v_lshlrev_b32_e32 v138, 3, v22
	v_lshlrev_b32_e32 v140, 3, v24
	v_lshlrev_b32_e32 v142, 3, v26
	v_lshlrev_b32_e32 v144, 3, v28
	v_lshlrev_b32_e32 v146, 3, v30
	v_lshlrev_b32_e32 v148, 3, v32
	v_lshlrev_b32_e32 v150, 3, v34
	v_lshlrev_b32_e32 v152, 3, v36
	v_lshlrev_b32_e32 v154, 3, v38
	v_lshlrev_b32_e32 v156, 3, v40
	v_lshlrev_b32_e32 v158, 3, v42
	v_lshlrev_b32_e32 v170, 3, v44
	s_movk_i32 s16, 0x3000
	v_lshlrev_b32_e32 v172, 3, v46
	v_lshlrev_b32_e32 v174, 3, v48
	v_lshlrev_b32_e32 v176, 3, v50
	v_lshlrev_b32_e32 v178, 3, v52
	v_lshlrev_b32_e32 v180, 3, v54
	v_lshlrev_b32_e32 v182, 3, v56
	v_lshlrev_b32_e32 v184, 3, v58
	v_lshlrev_b32_e32 v186, 3, v60
	v_lshlrev_b32_e32 v188, 1, v0
	v_lshlrev_b32_e32 v190, 1, v2
	s_mov_b32 s17, 0x6e00000
	s_mov_b32 s18, 0x7e00000
	s_mov_b32 s19, 0x7c000
	v_add_u32_e32 v242, v11, v5
	v_add_u32_e32 v243, v11, v7
	v_add_u32_e32 v244, v9, v13
	s_mov_b32 s20, s2

; __device__ __forceinline__ unsigned xb_ld(unsigned* p)              { return __hip_atomic_load(p, __ATOMIC_RELAXED, __HIP_MEMORY_SCOPE_AGENT); }
; __device__ __forceinline__ unsigned xb_add(unsigned* p, unsigned v) { return __hip_atomic_fetch_add(p, v, __ATOMIC_RELAXED, __HIP_MEMORY_SCOPE_AGENT); }
; #define XB_SPIN(cond, bar) do { unsigned _sp = 0; while (cond) { __builtin_amdgcn_s_sleep(1); \
;     if ((++_sp & 255u) == 0u) { if (xb_ld(&(bar)[XB_TMO])) break; if (_sp > XB_SPIN_CAP) { atomicAdd(&(bar)[XB_TMO], 1u); break; } } } } while (0)
; __device__ __forceinline__ void xcd_barrier(const XcdBarrier& b) {
;     ...
;         const unsigned old = xb_add(&bar[XB_XSUB(b.x)], 1u);
;         const unsigned gen = old / nloc;
;         if (old + 1u == (gen + 1u) * nloc) {
;             __builtin_amdgcn_fence(__ATOMIC_RELEASE, "agent");
;             asm volatile("s_waitcnt vmcnt(0)" ::: "memory");
;             const unsigned og = xb_add(&bar[XB_TOP], 1u);
;             const unsigned tg = og / nx;
;             if (og + 1u == (tg + 1u) * nx) xb_add(&bar[XB_TOPGEN], 1u);
;             else XB_SPIN(xb_ld(&bar[XB_TOPGEN]) == tg, bar);
;             __builtin_amdgcn_fence(__ATOMIC_ACQUIRE, "agent");
;             xb_add(&bar[XB_XGEN(b.x)], 1u);
;             asm volatile("s_waitcnt vmcnt(0)" ::: "memory");
;         } else {
;             XB_SPIN(xb_ld(&bar[XB_XGEN(b.x)]) == gen, bar);
;             __builtin_amdgcn_fence(__ATOMIC_ACQUIRE, "agent");
.LBB0_359:
	s_or_b64 exec, exec, s[8:9]
	v_cvt_f32_u32_e32 v4, v2
	s_waitcnt vmcnt(0)
	v_readfirstlane_b32 s6, v3
	v_sub_u32_e32 v3, 0, v2
	v_rcp_iflag_f32_e32 v4, v4
	v_add_u32_e32 v5, s6, v1
	v_mul_f32_e32 v4, 0x4f7ffffe, v4
	v_cvt_u32_f32_e32 v4, v4
	v_mul_lo_u32 v1, v3, v4
	v_mul_hi_u32 v1, v4, v1
	v_add_u32_e32 v1, v4, v1
	v_mul_hi_u32 v1, v5, v1
	v_mul_lo_u32 v3, v1, v2
	v_sub_u32_e32 v3, v5, v3
	v_add_u32_e32 v4, 1, v1
	v_cmp_ge_u32_e32 vcc, v3, v2
	s_nop 1
	v_cndmask_b32_e32 v1, v1, v4, vcc
	v_sub_u32_e32 v4, v3, v2
	v_cndmask_b32_e32 v3, v3, v4, vcc
	v_add_u32_e32 v4, 1, v1
	v_cmp_ge_u32_e32 vcc, v3, v2
	v_add_u32_e32 v3, 1, v5
	s_nop 0
	v_cndmask_b32_e32 v1, v1, v4, vcc
	v_mul_lo_u32 v4, v2, v1
	v_add_u32_e32 v2, v4, v2
	v_cmp_ne_u32_e32 vcc, v3, v2
	s_and_saveexec_b64 s[6:7], vcc
	s_xor_b64 s[6:7], exec, s[6:7]
	s_cbranch_execz .LBB0_373
	s_waitcnt lgkmcnt(0)
	buffer_inv sc1
	v_mul_u32_u24_e32 v1, 4, v0
	v_mov_b32_e32 v0, 0
	s_add_u32 s12, s58, 0xc3400
	s_addc_u32 s13, s59, 0
	global_load_dword v0, v0, s[12:13] sc1
	s_waitcnt vmcnt(0)
	v_cmp_lt_u32_e32 vcc, v0, v1
	s_and_saveexec_b64 s[8:9], vcc
	s_cbranch_execz .LBB0_372
	s_add_u32 s10, s58, 0xc0200
	s_addc_u32 s11, s59, 0
	s_mov_b32 s24, 1
	s_mov_b64 s[14:15], 0
	v_mov_b32_e32 v0, 0
	s_branch .LBB0_363

; __device__ __forceinline__ unsigned xb_ld(unsigned* p)              { return __hip_atomic_load(p, __ATOMIC_RELAXED, __HIP_MEMORY_SCOPE_AGENT); }
; __device__ __forceinline__ unsigned xb_add(unsigned* p, unsigned v) { return __hip_atomic_fetch_add(p, v, __ATOMIC_RELAXED, __HIP_MEMORY_SCOPE_AGENT); }
; #define XB_SPIN(cond, bar) do { unsigned _sp = 0; while (cond) { __builtin_amdgcn_s_sleep(1); \
;     if ((++_sp & 255u) == 0u) { if (xb_ld(&(bar)[XB_TMO])) break; if (_sp > XB_SPIN_CAP) { atomicAdd(&(bar)[XB_TMO], 1u); break; } } } } while (0)
; __device__ __forceinline__ void xcd_barrier(const XcdBarrier& b) {
;     ...
;             xb_add(&bar[XB_XGEN(b.x)], 1u);
;             asm volatile("s_waitcnt vmcnt(0)" ::: "memory");
;         } else {
;             XB_SPIN(xb_ld(&bar[XB_XGEN(b.x)]) == gen, bar);
;             __builtin_amdgcn_fence(__ATOMIC_ACQUIRE, "agent");
;             asm volatile("s_waitcnt vmcnt(0)" ::: "memory");
;         }
;     }
;     __syncthreads();
; }
.LBB0_392:
	s_or_b64 exec, exec, s[8:9]
.LBB0_393:
	s_or_b64 exec, exec, s[0:1]
	v_mov_b32_e32 v0, 0x23f30
	ds_read_b64 v[0:1], v0
	s_waitcnt lgkmcnt(0)
	v_readfirstlane_b32 s100, v0
	v_readfirstlane_b32 s101, v1
	s_nop 3
	s_cmp_eq_u32 s101, 1
	s_cbranch_scc0 .Lxb_norelabel
	s_lshl_b32 s100, s100, 3
	s_or_b32 s2, s100, s3

; __device__ __forceinline__ unsigned xb_ld(unsigned* p)              { return __hip_atomic_load(p, __ATOMIC_RELAXED, __HIP_MEMORY_SCOPE_AGENT); }
; __device__ __forceinline__ unsigned xb_add(unsigned* p, unsigned v) { return __hip_atomic_fetch_add(p, v, __ATOMIC_RELAXED, __HIP_MEMORY_SCOPE_AGENT); }
; #define XB_SPIN(cond, bar) do { unsigned _sp = 0; while (cond) { __builtin_amdgcn_s_sleep(1); \
;     if ((++_sp & 255u) == 0u) { if (xb_ld(&(bar)[XB_TMO])) break; if (_sp > XB_SPIN_CAP) { atomicAdd(&(bar)[XB_TMO], 1u); break; } } } } while (0)
; __device__ __forceinline__ void xcd_barrier(const XcdBarrier& b) {
;     ...
;         const unsigned old = xb_add(&bar[XB_XSUB(b.x)], 1u);
;         const unsigned gen = old / nloc;
;         if (old + 1u == (gen + 1u) * nloc) {
;             __builtin_amdgcn_fence(__ATOMIC_RELEASE, "agent");
;             asm volatile("s_waitcnt vmcnt(0)" ::: "memory");
;             const unsigned og = xb_add(&bar[XB_TOP], 1u);
;             const unsigned tg = og / nx;
;             if (og + 1u == (tg + 1u) * nx) xb_add(&bar[XB_TOPGEN], 1u);
;             else XB_SPIN(xb_ld(&bar[XB_TOPGEN]) == tg, bar);
;             __builtin_amdgcn_fence(__ATOMIC_ACQUIRE, "agent");
;             xb_add(&bar[XB_XGEN(b.x)], 1u);
;             asm volatile("s_waitcnt vmcnt(0)" ::: "memory");
;         } else {
;             XB_SPIN(xb_ld(&bar[XB_XGEN(b.x)]) == gen, bar);
;             __builtin_amdgcn_fence(__ATOMIC_ACQUIRE, "agent");
.LBB0_453:
	s_or_b64 exec, exec, s[12:13]
	v_cvt_f32_u32_e32 v4, v2
	s_waitcnt vmcnt(0)
	v_readfirstlane_b32 s8, v3
	v_sub_u32_e32 v3, 0, v2
	v_rcp_iflag_f32_e32 v4, v4
	v_add_u32_e32 v5, s8, v1
	v_mul_f32_e32 v4, 0x4f7ffffe, v4
	v_cvt_u32_f32_e32 v4, v4
	v_mul_lo_u32 v1, v3, v4
	v_mul_hi_u32 v1, v4, v1
	v_add_u32_e32 v1, v4, v1
	v_mul_hi_u32 v1, v5, v1
	v_mul_lo_u32 v3, v1, v2
	v_sub_u32_e32 v3, v5, v3
	v_add_u32_e32 v4, 1, v1
	v_cmp_ge_u32_e32 vcc, v3, v2
	s_nop 1
	v_cndmask_b32_e32 v1, v1, v4, vcc
	v_sub_u32_e32 v4, v3, v2
	v_cndmask_b32_e32 v3, v3, v4, vcc
	v_add_u32_e32 v4, 1, v1
	v_cmp_ge_u32_e32 vcc, v3, v2
	v_add_u32_e32 v3, 1, v5
	s_nop 0
	v_cndmask_b32_e32 v1, v1, v4, vcc
	v_mul_lo_u32 v4, v2, v1
	v_add_u32_e32 v2, v4, v2
	v_cmp_ne_u32_e32 vcc, v3, v2
	s_and_saveexec_b64 s[8:9], vcc
	s_xor_b64 s[8:9], exec, s[8:9]
	s_cbranch_execz .LBB0_467
	s_waitcnt lgkmcnt(0)
	buffer_inv sc1
	v_mov_b32_e32 v0, 0x2000
	global_load_dword v0, v0, s[6:7] offset:1024 sc1
	s_add_u32 s16, s6, 0x2400
	s_addc_u32 s17, s7, 0
	s_waitcnt vmcnt(0)
	v_cmp_le_u32_e32 vcc, v0, v1
	s_and_saveexec_b64 s[12:13], vcc
	s_cbranch_execz .LBB0_466
	s_add_u32 s14, s58, 0xc0200
	s_addc_u32 s15, s59, 0
	s_mov_b32 s28, 1
	s_mov_b64 s[18:19], 0
	v_mov_b32_e32 v0, 0
	s_branch .LBB0_457

; __device__ __forceinline__ unsigned xb_ld(unsigned* p)              { return __hip_atomic_load(p, __ATOMIC_RELAXED, __HIP_MEMORY_SCOPE_AGENT); }
; #define XB_SPIN(cond, bar) do { unsigned _sp = 0; while (cond) { __builtin_amdgcn_s_sleep(1); \
;     if ((++_sp & 255u) == 0u) { if (xb_ld(&(bar)[XB_TMO])) break; if (_sp > XB_SPIN_CAP) { atomicAdd(&(bar)[XB_TMO], 1u); break; } } } } while (0)
; __device__ __forceinline__ void xcd_barrier(const XcdBarrier& b) {
;     ...
;             XB_SPIN(xb_ld(&bar[XB_XGEN(b.x)]) == gen, bar);
.LBB0_461:
	global_load_dword v2, v0, s[16:17] sc1
	s_add_i32 s28, s28, 1
	s_mov_b64 s[24:25], -1
	s_waitcnt vmcnt(0)
	v_cmp_gt_u32_e32 vcc, v2, v1
	s_orn2_b64 s[22:23], vcc, exec
	s_branch .LBB0_456

; __device__ __forceinline__ unsigned xb_ld(unsigned* p)              { return __hip_atomic_load(p, __ATOMIC_RELAXED, __HIP_MEMORY_SCOPE_AGENT); }
; __device__ __forceinline__ unsigned xb_add(unsigned* p, unsigned v) { return __hip_atomic_fetch_add(p, v, __ATOMIC_RELAXED, __HIP_MEMORY_SCOPE_AGENT); }
; #define XB_SPIN(cond, bar) do { unsigned _sp = 0; while (cond) { __builtin_amdgcn_s_sleep(1); \
;     if ((++_sp & 255u) == 0u) { if (xb_ld(&(bar)[XB_TMO])) break; if (_sp > XB_SPIN_CAP) { atomicAdd(&(bar)[XB_TMO], 1u); break; } } } } while (0)
; __device__ __forceinline__ void xcd_barrier(const XcdBarrier& b) {
;     ...
;             const unsigned og = xb_add(&bar[XB_TOP], 1u);
;             const unsigned tg = og / nx;
;             if (og + 1u == (tg + 1u) * nx) xb_add(&bar[XB_TOPGEN], 1u);
;             else XB_SPIN(xb_ld(&bar[XB_TOPGEN]) == tg, bar);
.LBB0_470:
	s_or_b64 exec, exec, s[12:13]
	v_cvt_f32_u32_e32 v3, v0
	s_waitcnt vmcnt(0)
	v_readfirstlane_b32 s8, v2
	s_add_u32 s12, s58, 0xc3500
	s_addc_u32 s13, s59, 0
	v_rcp_iflag_f32_e32 v3, v3
	v_add_u32_e32 v1, s8, v1
	v_add_u32_e32 v4, 1, v1
	s_mov_b64 s[14:15], -1
	v_mul_f32_e32 v2, 0x4f7ffffe, v3
	v_cvt_u32_f32_e32 v2, v2
	v_sub_u32_e32 v3, 0, v0
	v_mul_lo_u32 v3, v3, v2
	v_mul_hi_u32 v3, v2, v3
	v_add_u32_e32 v2, v2, v3
	v_mul_hi_u32 v2, v1, v2
	v_mul_lo_u32 v3, v2, v0
	v_sub_u32_e32 v1, v1, v3
	v_add_u32_e32 v5, 1, v2
	v_cmp_ge_u32_e32 vcc, v1, v0
	v_sub_u32_e32 v3, v1, v0
	s_nop 0
	v_cndmask_b32_e32 v2, v2, v5, vcc
	v_cndmask_b32_e32 v1, v1, v3, vcc
	v_add_u32_e32 v3, 1, v2
	v_cmp_ge_u32_e32 vcc, v1, v0
	s_nop 1
	v_cndmask_b32_e32 v2, v2, v3, vcc
	v_mul_lo_u32 v1, v0, v2
	v_add_u32_e32 v0, v1, v0
	v_cmp_ne_u32_e32 vcc, v4, v0
	v_mov_b32_e32 v2, v0
	v_mov_b64_e32 v[0:1], s[12:13]
	s_and_saveexec_b64 s[8:9], vcc
	s_cbranch_execz .LBB0_482
	s_sub_u32 s12, s12, 0x100
	s_subb_u32 s13, s13, 0
	v_mov_b32_e32 v0, 0
	global_load_dword v1, v0, s[12:13] sc1
	s_mov_b64 s[18:19], 0
	s_waitcnt vmcnt(0)
	v_cmp_lt_u32_e32 vcc, v1, v2
	s_and_saveexec_b64 s[16:17], vcc
	s_cbranch_execz .LBB0_481
	s_add_u32 s14, s58, 0xc0200
	s_addc_u32 s15, s59, 0
	s_mov_b32 s28, 1
	s_branch .LBB0_474

; __device__ __forceinline__ unsigned xb_ld(unsigned* p)              { return __hip_atomic_load(p, __ATOMIC_RELAXED, __HIP_MEMORY_SCOPE_AGENT); }
; __device__ __forceinline__ unsigned xb_add(unsigned* p, unsigned v) { return __hip_atomic_fetch_add(p, v, __ATOMIC_RELAXED, __HIP_MEMORY_SCOPE_AGENT); }
; #define XB_SPIN(cond, bar) do { unsigned _sp = 0; while (cond) { __builtin_amdgcn_s_sleep(1); \
;     if ((++_sp & 255u) == 0u) { if (xb_ld(&(bar)[XB_TMO])) break; if (_sp > XB_SPIN_CAP) { atomicAdd(&(bar)[XB_TMO], 1u); break; } } } } while (0)
; __device__ __forceinline__ void xcd_barrier(const XcdBarrier& b) {
;     ...
;         const unsigned old = xb_add(&bar[XB_XSUB(b.x)], 1u);
;         const unsigned gen = old / nloc;
;         if (old + 1u == (gen + 1u) * nloc) {
;             __builtin_amdgcn_fence(__ATOMIC_RELEASE, "agent");
;             asm volatile("s_waitcnt vmcnt(0)" ::: "memory");
;             const unsigned og = xb_add(&bar[XB_TOP], 1u);
;             const unsigned tg = og / nx;
;             if (og + 1u == (tg + 1u) * nx) xb_add(&bar[XB_TOPGEN], 1u);
;             else XB_SPIN(xb_ld(&bar[XB_TOPGEN]) == tg, bar);
;             __builtin_amdgcn_fence(__ATOMIC_ACQUIRE, "agent");
;             xb_add(&bar[XB_XGEN(b.x)], 1u);
;             asm volatile("s_waitcnt vmcnt(0)" ::: "memory");
;         } else {
;             XB_SPIN(xb_ld(&bar[XB_XGEN(b.x)]) == gen, bar);
;             __builtin_amdgcn_fence(__ATOMIC_ACQUIRE, "agent");
.LBB0_529:
	s_or_b64 exec, exec, s[10:11]
	v_cvt_f32_u32_e32 v4, v2
	s_waitcnt vmcnt(0)
	v_readfirstlane_b32 s6, v3
	v_sub_u32_e32 v3, 0, v2
	v_rcp_iflag_f32_e32 v4, v4
	v_add_u32_e32 v5, s6, v1
	v_mul_f32_e32 v4, 0x4f7ffffe, v4
	v_cvt_u32_f32_e32 v4, v4
	v_mul_lo_u32 v1, v3, v4
	v_mul_hi_u32 v1, v4, v1
	v_add_u32_e32 v1, v4, v1
	v_mul_hi_u32 v1, v5, v1
	v_mul_lo_u32 v3, v1, v2
	v_sub_u32_e32 v3, v5, v3
	v_add_u32_e32 v4, 1, v1
	v_cmp_ge_u32_e32 vcc, v3, v2
	s_nop 1
	v_cndmask_b32_e32 v1, v1, v4, vcc
	v_sub_u32_e32 v4, v3, v2
	v_cndmask_b32_e32 v3, v3, v4, vcc
	v_add_u32_e32 v4, 1, v1
	v_cmp_ge_u32_e32 vcc, v3, v2
	v_add_u32_e32 v3, 1, v5
	s_nop 0
	v_cndmask_b32_e32 v1, v1, v4, vcc
	v_mul_lo_u32 v4, v2, v1
	v_add_u32_e32 v2, v4, v2
	v_cmp_ne_u32_e32 vcc, v3, v2
	s_and_saveexec_b64 s[6:7], vcc
	s_xor_b64 s[6:7], exec, s[6:7]
	s_cbranch_execz .LBB0_543
	s_waitcnt lgkmcnt(0)
	buffer_inv sc1
	v_mov_b32_e32 v0, 0x2000
	global_load_dword v0, v0, s[4:5] offset:1024 sc1
	s_add_u32 s14, s4, 0x2400
	s_addc_u32 s15, s5, 0
	s_waitcnt vmcnt(0)
	v_cmp_le_u32_e32 vcc, v0, v1
	s_and_saveexec_b64 s[10:11], vcc
	s_cbranch_execz .LBB0_542
	s_add_u32 s12, s58, 0xc0200
	s_addc_u32 s13, s59, 0
	s_mov_b32 s26, 1
	s_mov_b64 s[16:17], 0
	v_mov_b32_e32 v0, 0
	s_branch .LBB0_533

; __device__ __forceinline__ unsigned xb_ld(unsigned* p)              { return __hip_atomic_load(p, __ATOMIC_RELAXED, __HIP_MEMORY_SCOPE_AGENT); }
; #define XB_SPIN(cond, bar) do { unsigned _sp = 0; while (cond) { __builtin_amdgcn_s_sleep(1); \
;     if ((++_sp & 255u) == 0u) { if (xb_ld(&(bar)[XB_TMO])) break; if (_sp > XB_SPIN_CAP) { atomicAdd(&(bar)[XB_TMO], 1u); break; } } } } while (0)
; __device__ __forceinline__ void xcd_barrier(const XcdBarrier& b) {
;     ...
;             XB_SPIN(xb_ld(&bar[XB_XGEN(b.x)]) == gen, bar);
.LBB0_537:
	global_load_dword v2, v0, s[14:15] sc1
	s_add_i32 s26, s26, 1
	s_mov_b64 s[22:23], -1
	s_waitcnt vmcnt(0)
	v_cmp_gt_u32_e32 vcc, v2, v1
	s_orn2_b64 s[20:21], vcc, exec
	s_branch .LBB0_532

; __device__ __forceinline__ unsigned xb_ld(unsigned* p)              { return __hip_atomic_load(p, __ATOMIC_RELAXED, __HIP_MEMORY_SCOPE_AGENT); }
; __device__ __forceinline__ unsigned xb_add(unsigned* p, unsigned v) { return __hip_atomic_fetch_add(p, v, __ATOMIC_RELAXED, __HIP_MEMORY_SCOPE_AGENT); }
; #define XB_SPIN(cond, bar) do { unsigned _sp = 0; while (cond) { __builtin_amdgcn_s_sleep(1); \
;     if ((++_sp & 255u) == 0u) { if (xb_ld(&(bar)[XB_TMO])) break; if (_sp > XB_SPIN_CAP) { atomicAdd(&(bar)[XB_TMO], 1u); break; } } } } while (0)
; __device__ __forceinline__ void xcd_barrier(const XcdBarrier& b) {
;     ...
;             const unsigned og = xb_add(&bar[XB_TOP], 1u);
;             const unsigned tg = og / nx;
;             if (og + 1u == (tg + 1u) * nx) xb_add(&bar[XB_TOPGEN], 1u);
;             else XB_SPIN(xb_ld(&bar[XB_TOPGEN]) == tg, bar);
.LBB0_546:
	s_or_b64 exec, exec, s[10:11]
	v_cvt_f32_u32_e32 v3, v0
	s_waitcnt vmcnt(0)
	v_readfirstlane_b32 s6, v2
	s_add_u32 s10, s58, 0xc3500
	s_addc_u32 s11, s59, 0
	v_rcp_iflag_f32_e32 v3, v3
	v_add_u32_e32 v1, s6, v1
	v_add_u32_e32 v4, 1, v1
	s_mov_b64 s[12:13], -1
	v_mul_f32_e32 v2, 0x4f7ffffe, v3
	v_cvt_u32_f32_e32 v2, v2
	v_sub_u32_e32 v3, 0, v0
	v_mul_lo_u32 v3, v3, v2
	v_mul_hi_u32 v3, v2, v3
	v_add_u32_e32 v2, v2, v3
	v_mul_hi_u32 v2, v1, v2
	v_mul_lo_u32 v3, v2, v0
	v_sub_u32_e32 v1, v1, v3
	v_add_u32_e32 v5, 1, v2
	v_cmp_ge_u32_e32 vcc, v1, v0
	v_sub_u32_e32 v3, v1, v0
	s_nop 0
	v_cndmask_b32_e32 v2, v2, v5, vcc
	v_cndmask_b32_e32 v1, v1, v3, vcc
	v_add_u32_e32 v3, 1, v2
	v_cmp_ge_u32_e32 vcc, v1, v0
	s_nop 1
	v_cndmask_b32_e32 v2, v2, v3, vcc
	v_mul_lo_u32 v1, v0, v2
	v_add_u32_e32 v0, v1, v0
	v_cmp_ne_u32_e32 vcc, v4, v0
	v_mov_b32_e32 v2, v0
	v_mov_b64_e32 v[0:1], s[10:11]
	s_and_saveexec_b64 s[6:7], vcc
	s_cbranch_execz .LBB0_558
	s_sub_u32 s10, s10, 0x100
	s_subb_u32 s11, s11, 0
	v_mov_b32_e32 v0, 0
	global_load_dword v1, v0, s[10:11] sc1
	s_mov_b64 s[16:17], 0
	s_waitcnt vmcnt(0)
	v_cmp_lt_u32_e32 vcc, v1, v2
	s_and_saveexec_b64 s[14:15], vcc
	s_cbranch_execz .LBB0_557
	s_add_u32 s12, s58, 0xc0200
	s_addc_u32 s13, s59, 0
	s_mov_b32 s26, 1
	s_branch .LBB0_550

; __device__ __forceinline__ unsigned xb_ld(unsigned* p)              { return __hip_atomic_load(p, __ATOMIC_RELAXED, __HIP_MEMORY_SCOPE_AGENT); }
; #define XB_SPIN(cond, bar) do { unsigned _sp = 0; while (cond) { __builtin_amdgcn_s_sleep(1); \
;     if ((++_sp & 255u) == 0u) { if (xb_ld(&(bar)[XB_TMO])) break; if (_sp > XB_SPIN_CAP) { atomicAdd(&(bar)[XB_TMO], 1u); break; } } } } while (0)
; __device__ __forceinline__ void xcd_barrier(const XcdBarrier& b) {
;     ...
;             else XB_SPIN(xb_ld(&bar[XB_TOPGEN]) == tg, bar);
.LBB0_554:
	global_load_dword v1, v0, s[10:11] sc1
	s_add_i32 s26, s26, 1
	s_mov_b64 s[20:21], -1
	s_waitcnt vmcnt(0)
	v_cmp_ge_u32_e32 vcc, v1, v2
	s_orn2_b64 s[24:25], vcc, exec
	s_branch .LBB0_549

; __device__ __forceinline__ unsigned xb_ld(unsigned* p)              { return __hip_atomic_load(p, __ATOMIC_RELAXED, __HIP_MEMORY_SCOPE_AGENT); }
; __device__ __forceinline__ unsigned xb_add(unsigned* p, unsigned v) { return __hip_atomic_fetch_add(p, v, __ATOMIC_RELAXED, __HIP_MEMORY_SCOPE_AGENT); }
; #define XB_SPIN(cond, bar) do { unsigned _sp = 0; while (cond) { __builtin_amdgcn_s_sleep(1); \
;     if ((++_sp & 255u) == 0u) { if (xb_ld(&(bar)[XB_TMO])) break; if (_sp > XB_SPIN_CAP) { atomicAdd(&(bar)[XB_TMO], 1u); break; } } } } while (0)
; __device__ __forceinline__ void xcd_barrier(const XcdBarrier& b) {
;     ...
;         const unsigned old = xb_add(&bar[XB_XSUB(b.x)], 1u);
;         const unsigned gen = old / nloc;
;         if (old + 1u == (gen + 1u) * nloc) {
;             __builtin_amdgcn_fence(__ATOMIC_RELEASE, "agent");
;             asm volatile("s_waitcnt vmcnt(0)" ::: "memory");
;             const unsigned og = xb_add(&bar[XB_TOP], 1u);
;             const unsigned tg = og / nx;
;             if (og + 1u == (tg + 1u) * nx) xb_add(&bar[XB_TOPGEN], 1u);
;             else XB_SPIN(xb_ld(&bar[XB_TOPGEN]) == tg, bar);
;             __builtin_amdgcn_fence(__ATOMIC_ACQUIRE, "agent");
;             xb_add(&bar[XB_XGEN(b.x)], 1u);
;             asm volatile("s_waitcnt vmcnt(0)" ::: "memory");
;         } else {
;             XB_SPIN(xb_ld(&bar[XB_XGEN(b.x)]) == gen, bar);
;             __builtin_amdgcn_fence(__ATOMIC_ACQUIRE, "agent");
.LBB0_623:
	s_or_b64 exec, exec, s[14:15]
	v_cvt_f32_u32_e32 v4, v2
	s_waitcnt vmcnt(0)
	v_readfirstlane_b32 s12, v3
	v_sub_u32_e32 v3, 0, v2
	v_rcp_iflag_f32_e32 v4, v4
	v_add_u32_e32 v5, s12, v1
	v_mul_f32_e32 v4, 0x4f7ffffe, v4
	v_cvt_u32_f32_e32 v4, v4
	v_mul_lo_u32 v1, v3, v4
	v_mul_hi_u32 v1, v4, v1
	v_add_u32_e32 v1, v4, v1
	v_mul_hi_u32 v1, v5, v1
	v_mul_lo_u32 v3, v1, v2
	v_sub_u32_e32 v3, v5, v3
	v_add_u32_e32 v4, 1, v1
	v_cmp_ge_u32_e32 vcc, v3, v2
	s_nop 1
	v_cndmask_b32_e32 v1, v1, v4, vcc
	v_sub_u32_e32 v4, v3, v2
	v_cndmask_b32_e32 v3, v3, v4, vcc
	v_add_u32_e32 v4, 1, v1
	v_cmp_ge_u32_e32 vcc, v3, v2
	v_add_u32_e32 v3, 1, v5
	s_nop 0
	v_cndmask_b32_e32 v1, v1, v4, vcc
	v_mul_lo_u32 v4, v2, v1
	v_add_u32_e32 v2, v4, v2
	v_cmp_ne_u32_e32 vcc, v3, v2
	s_and_saveexec_b64 s[12:13], vcc
	s_xor_b64 s[12:13], exec, s[12:13]
	s_cbranch_execz .LBB0_637
	s_waitcnt lgkmcnt(0)
	buffer_inv sc1
	s_cmp_eq_u32 s101, 1
	s_cselect_b32 s18, 5, 7
	v_mul_u32_u24_e32 v1, s18, v0
	v_mov_b32_e32 v0, 0
	s_add_u32 s18, s58, 0xc3400
	s_addc_u32 s19, s59, 0
	global_load_dword v0, v0, s[18:19] sc1
	s_waitcnt vmcnt(0)
	v_cmp_lt_u32_e32 vcc, v0, v1
	s_and_saveexec_b64 s[14:15], vcc
	s_cbranch_execz .LBB0_636
	s_add_u32 s16, s58, 0xc0200
	s_addc_u32 s17, s59, 0
	s_mov_b32 s30, 1
	s_mov_b64 s[20:21], 0
	v_mov_b32_e32 v0, 0
	s_branch .LBB0_627

; __device__ __forceinline__ unsigned xb_ld(unsigned* p)              { return __hip_atomic_load(p, __ATOMIC_RELAXED, __HIP_MEMORY_SCOPE_AGENT); }
; #define XB_SPIN(cond, bar) do { unsigned _sp = 0; while (cond) { __builtin_amdgcn_s_sleep(1); \
;     if ((++_sp & 255u) == 0u) { if (xb_ld(&(bar)[XB_TMO])) break; if (_sp > XB_SPIN_CAP) { atomicAdd(&(bar)[XB_TMO], 1u); break; } } } } while (0)
; __device__ __forceinline__ void xcd_barrier(const XcdBarrier& b) {
;     ...
;             XB_SPIN(xb_ld(&bar[XB_XGEN(b.x)]) == gen, bar);
.LBB0_631:
	global_load_dword v2, v0, s[18:19] sc1
	s_add_i32 s30, s30, 1
	s_mov_b64 s[26:27], -1
	s_waitcnt vmcnt(0)
	v_cmp_ge_u32_e32 vcc, v2, v1
	s_orn2_b64 s[24:25], vcc, exec
	s_branch .LBB0_626

; __device__ __forceinline__ unsigned xb_ld(unsigned* p)              { return __hip_atomic_load(p, __ATOMIC_RELAXED, __HIP_MEMORY_SCOPE_AGENT); }
; __device__ __forceinline__ unsigned xb_add(unsigned* p, unsigned v) { return __hip_atomic_fetch_add(p, v, __ATOMIC_RELAXED, __HIP_MEMORY_SCOPE_AGENT); }
; #define XB_SPIN(cond, bar) do { unsigned _sp = 0; while (cond) { __builtin_amdgcn_s_sleep(1); \
;     if ((++_sp & 255u) == 0u) { if (xb_ld(&(bar)[XB_TMO])) break; if (_sp > XB_SPIN_CAP) { atomicAdd(&(bar)[XB_TMO], 1u); break; } } } } while (0)
; __device__ __forceinline__ void xcd_barrier(const XcdBarrier& b) {
;     ...
;             const unsigned og = xb_add(&bar[XB_TOP], 1u);
;             const unsigned tg = og / nx;
;             if (og + 1u == (tg + 1u) * nx) xb_add(&bar[XB_TOPGEN], 1u);
;             else XB_SPIN(xb_ld(&bar[XB_TOPGEN]) == tg, bar);
.LBB0_640:
	s_or_b64 exec, exec, s[14:15]
	v_cvt_f32_u32_e32 v3, v0
	s_waitcnt vmcnt(0)
	v_readfirstlane_b32 s12, v2
	s_add_u32 s14, s58, 0xc3500
	s_addc_u32 s15, s59, 0
	v_rcp_iflag_f32_e32 v3, v3
	v_add_u32_e32 v1, s12, v1
	v_add_u32_e32 v4, 1, v1
	s_mov_b64 s[16:17], -1
	v_mul_f32_e32 v2, 0x4f7ffffe, v3
	v_cvt_u32_f32_e32 v2, v2
	v_sub_u32_e32 v3, 0, v0
	v_mul_lo_u32 v3, v3, v2
	v_mul_hi_u32 v3, v2, v3
	v_add_u32_e32 v2, v2, v3
	v_mul_hi_u32 v2, v1, v2
	v_mul_lo_u32 v3, v2, v0
	v_sub_u32_e32 v1, v1, v3
	v_add_u32_e32 v5, 1, v2
	v_cmp_ge_u32_e32 vcc, v1, v0
	v_sub_u32_e32 v3, v1, v0
	s_nop 0
	v_cndmask_b32_e32 v2, v2, v5, vcc
	v_cndmask_b32_e32 v1, v1, v3, vcc
	v_add_u32_e32 v3, 1, v2
	v_cmp_ge_u32_e32 vcc, v1, v0
	s_nop 1
	v_cndmask_b32_e32 v2, v2, v3, vcc
	v_mul_lo_u32 v1, v0, v2
	v_add_u32_e32 v0, v1, v0
	v_cmp_ne_u32_e32 vcc, v4, v0
	v_mov_b32_e32 v2, v0
	v_mov_b64_e32 v[0:1], s[14:15]
	s_and_saveexec_b64 s[12:13], vcc
	s_cbranch_execz .LBB0_652
	s_sub_u32 s14, s14, 0x100
	s_subb_u32 s15, s15, 0
	v_mov_b32_e32 v0, 0
	global_load_dword v1, v0, s[14:15] sc1
	s_mov_b64 s[20:21], 0
	s_waitcnt vmcnt(0)
	v_cmp_lt_u32_e32 vcc, v1, v2
	s_and_saveexec_b64 s[18:19], vcc
	s_cbranch_execz .LBB0_651
	s_add_u32 s16, s58, 0xc0200
	s_addc_u32 s17, s59, 0
	s_mov_b32 s30, 1
	s_branch .LBB0_644

; __device__ __forceinline__ unsigned xb_ld(unsigned* p)              { return __hip_atomic_load(p, __ATOMIC_RELAXED, __HIP_MEMORY_SCOPE_AGENT); }
; #define XB_SPIN(cond, bar) do { unsigned _sp = 0; while (cond) { __builtin_amdgcn_s_sleep(1); \
;     if ((++_sp & 255u) == 0u) { if (xb_ld(&(bar)[XB_TMO])) break; if (_sp > XB_SPIN_CAP) { atomicAdd(&(bar)[XB_TMO], 1u); break; } } } } while (0)
; __device__ __forceinline__ void xcd_barrier(const XcdBarrier& b) {
;     ...
;             else XB_SPIN(xb_ld(&bar[XB_TOPGEN]) == tg, bar);
.LBB0_648:
	global_load_dword v1, v0, s[14:15] sc1
	s_add_i32 s30, s30, 1
	s_mov_b64 s[24:25], -1
	s_waitcnt vmcnt(0)
	v_cmp_ge_u32_e32 vcc, v1, v2
	s_orn2_b64 s[28:29], vcc, exec
	s_branch .LBB0_643

; #define PG8_STAGE(bufoff, gbase, voff) do { _Pragma("unroll") for (int _i = 0; _i < 2; ++_i) \
;         __builtin_amdgcn_global_load_lds((const unsigned*)((const char*)(gbase) + (voff)[_i]), (PG8_LAS unsigned*)(lds + (bufoff) + ldsw + _i * 8192), 16, 0, 0); } while (0)
; #define PG8_WAIT_V(n) asm volatile("s_waitcnt vmcnt(" #n ")" ::: "memory")
; #define PG8_BAR __builtin_amdgcn_s_barrier()
; __device__ __forceinline__ unsigned xb_ld(unsigned* p)              { return __hip_atomic_load(p, __ATOMIC_RELAXED, __HIP_MEMORY_SCOPE_AGENT); }
; __device__ __forceinline__ unsigned xb_add(unsigned* p, unsigned v) { return __hip_atomic_fetch_add(p, v, __ATOMIC_RELAXED, __HIP_MEMORY_SCOPE_AGENT); }
; #define XB_SPIN(cond, bar) do { unsigned _sp = 0; while (cond) { __builtin_amdgcn_s_sleep(1); \
;     if ((++_sp & 255u) == 0u) { if (xb_ld(&(bar)[XB_TMO])) break; if (_sp > XB_SPIN_CAP) { atomicAdd(&(bar)[XB_TMO], 1u); break; } } } } while (0)
; template <class Epi, class Sched, bool ALIGN_EPI = false, bool SP2 = false, bool F16 = false>
; __device__ __forceinline__ void gemm_phase(PG8_LAS unsigned char* lds, const Gemm g, const Sched& S, const Epi& E) {
;     ...
;     const char* cA = (const char*)g.A + (size_t)cur.pm * tstep; const char* cB = (const char*)g.Bt + (size_t)cur.pn * tstep;
;     S.a_ready(cur);
;     if constexpr (SP2) {
;         PG8_STAGE(PG8_SB(0, 0), cB, voffB); PG8_STAGE(PG8_SB(0, 1), cB + hstep, voffB); PG8_STAGE(PG8_SA(0, 0), cA, voffA); PG8_STAGE(PG8_SA(0, 1), cA + hstep, voffA);
;         if (wr == 1) PG8_BAR;
;         PG8_WAIT_V(2); PG8_BAR;
;         PG8_STAGE(PG8_SB(1, 0), cB + kstep, voffB); PG8_STAGE(PG8_SA(1, 0), cA + kstep, voffA); PG8_STAGE(PG8_SB(1, 1), cB + hstep + kstep, voffB);
;         PG8_WAIT_V(6); PG8_BAR;
; __device__ __forceinline__ void xcd_barrier(const XcdBarrier& b) {
;     ...
;             xb_add(&bar[XB_XGEN(b.x)], 1u);
;             asm volatile("s_waitcnt vmcnt(0)" ::: "memory");
;         } else {
;             XB_SPIN(xb_ld(&bar[XB_XGEN(b.x)]) == gen, bar);
;             __builtin_amdgcn_fence(__ATOMIC_ACQUIRE, "agent");
;             asm volatile("s_waitcnt vmcnt(0)" ::: "memory");
;         }
;     }
;     __syncthreads();
; }
.LBB0_656:
	s_or_b64 exec, exec, s[14:15]
.LBB0_657:
	s_or_b64 exec, exec, s[4:5]
	s_cmpk_gt_i32 s2, 0xaff
	v_readfirstlane_b32 s5, v224
	s_waitcnt lgkmcnt(0)
	s_barrier
	s_cbranch_scc1 .LBB0_673
	s_add_u32 s33, s58, 0x1100000
	s_addc_u32 s34, s59, 0
	s_ashr_i32 s36, s2, 31
	s_lshr_b32 s4, s36, 29
	s_add_i32 s4, s2, s4
	s_lshr_b32 s12, s5, 6
	s_ashr_i32 s6, s4, 3
	s_and_b32 s4, s4, -8
	s_lshr_b32 s14, s5, 8
	s_lshl_b32 s35, s12, 10
	s_sub_i32 s4, s2, s4
	s_cmp_lt_i32 s4, 0
	s_movk_i32 s37, 0x161
	s_cselect_b32 s7, s37, 0x160
	s_mul_i32 s4, s4, s7
	s_add_i32 s4, s4, s6
	s_mul_hi_i32 s6, s4, 0x2e8ba2e9
	s_lshr_b32 s7, s6, 31
	s_ashr_i32 s6, s6, 5
	s_add_i32 s6, s6, s7
	s_lshl_b32 s7, s6, 3
	s_mulk_i32 s6, 0xb0
	s_sub_i32 s6, s4, s6
	s_sext_i32_i16 s4, s6
	s_bfe_u32 s4, s4, 0x3001c
	s_add_i32 s13, s6, s4
	s_sext_i32_i16 s4, s13
	s_and_b32 s13, s13, 0xfff8
	s_sub_i32 s6, s6, s13
	s_sext_i32_i16 s6, s6
	s_lshr_b32 s4, s4, 3
	s_add_i32 s24, s7, s6
	s_ashr_i32 s25, s24, 31
	s_bfe_i64 s[16:17], s[4:5], 0x100000
	s_lshl_b64 s[6:7], s[24:25], 19
	s_lshl_b64 s[16:17], s[16:17], 19
	s_add_u32 s28, s33, s16
	s_addc_u32 s29, s34, s17
	s_add_i32 s25, s35, 0
	s_add_i32 m0, s25, 0x10000
	v_mov_b32_e32 v165, 0
	global_load_lds_dwordx4 v164, s[28:29]
	s_add_i32 m0, s25, 0x12000
	s_add_u32 s16, s28, 0x40000
	global_load_lds_dwordx4 v168, s[28:29]
	s_addc_u32 s17, s29, 0
	s_add_i32 m0, s25, 0x14000
	v_mov_b32_e32 v169, v165
	global_load_lds_dwordx4 v164, s[16:17]
	s_add_i32 m0, s25, 0x16000
	s_add_u32 s26, s8, s6
	s_addc_u32 s27, s9, s7
	s_add_i32 s38, s25, 0x2000
	global_load_lds_dwordx4 v168, s[16:17]
	s_mov_b32 m0, s25
	s_add_u32 s6, s26, 0x40000
	global_load_lds_dwordx4 v162, s[26:27]
	s_mov_b32 m0, s38
	s_addc_u32 s7, s27, 0
	s_add_i32 s39, s25, 0x4000
	global_load_lds_dwordx4 v166, s[26:27]
	s_mov_b32 m0, s39
	s_add_i32 s40, s25, 0x6000
	global_load_lds_dwordx4 v162, s[6:7]
	s_mov_b32 m0, s40
	v_mov_b32_e32 v163, v165
	global_load_lds_dwordx4 v166, s[6:7]
	v_mov_b32_e32 v167, v165
	s_cmp_eq_u32 s14, 1
	s_mov_b32 s41, 0
	v_lshl_add_u64 v[6:7], s[28:29], 0, v[164:165]
	v_lshl_add_u64 v[4:5], s[28:29], 0, v[168:169]
	v_lshl_add_u64 v[0:1], s[26:27], 0, v[162:163]
	s_cselect_b64 s[6:7], -1, 0
	s_cmp_lg_u32 s14, 1
	v_lshl_add_u64 v[2:3], s[26:27], 0, v[166:167]
	s_cbranch_scc1 .LBB0_660
	s_barrier

; __device__ __forceinline__ unsigned xb_ld(unsigned* p)              { return __hip_atomic_load(p, __ATOMIC_RELAXED, __HIP_MEMORY_SCOPE_AGENT); }
; __device__ __forceinline__ unsigned xb_add(unsigned* p, unsigned v) { return __hip_atomic_fetch_add(p, v, __ATOMIC_RELAXED, __HIP_MEMORY_SCOPE_AGENT); }
; #define XB_SPIN(cond, bar) do { unsigned _sp = 0; while (cond) { __builtin_amdgcn_s_sleep(1); \
;     if ((++_sp & 255u) == 0u) { if (xb_ld(&(bar)[XB_TMO])) break; if (_sp > XB_SPIN_CAP) { atomicAdd(&(bar)[XB_TMO], 1u); break; } } } } while (0)
; __device__ __forceinline__ void xcd_barrier(const XcdBarrier& b) {
;     ...
;         const unsigned old = xb_add(&bar[XB_XSUB(b.x)], 1u);
;         const unsigned gen = old / nloc;
;         if (old + 1u == (gen + 1u) * nloc) {
;             __builtin_amdgcn_fence(__ATOMIC_RELEASE, "agent");
;             asm volatile("s_waitcnt vmcnt(0)" ::: "memory");
;             const unsigned og = xb_add(&bar[XB_TOP], 1u);
;             const unsigned tg = og / nx;
;             if (og + 1u == (tg + 1u) * nx) xb_add(&bar[XB_TOPGEN], 1u);
;             else XB_SPIN(xb_ld(&bar[XB_TOPGEN]) == tg, bar);
;             __builtin_amdgcn_fence(__ATOMIC_ACQUIRE, "agent");
;             xb_add(&bar[XB_XGEN(b.x)], 1u);
;             asm volatile("s_waitcnt vmcnt(0)" ::: "memory");
;         } else {
;             XB_SPIN(xb_ld(&bar[XB_XGEN(b.x)]) == gen, bar);
;             __builtin_amdgcn_fence(__ATOMIC_ACQUIRE, "agent");
.LBB0_691:
	s_or_b64 exec, exec, s[12:13]
	v_cvt_f32_u32_e32 v4, v2
	s_waitcnt vmcnt(0)
	v_readfirstlane_b32 s3, v3
	v_sub_u32_e32 v3, 0, v2
	v_rcp_iflag_f32_e32 v4, v4
	v_add_u32_e32 v5, s3, v1
	v_mul_f32_e32 v4, 0x4f7ffffe, v4
	v_cvt_u32_f32_e32 v4, v4
	v_mul_lo_u32 v1, v3, v4
	v_mul_hi_u32 v1, v4, v1
	v_add_u32_e32 v1, v4, v1
	v_mul_hi_u32 v1, v5, v1
	v_mul_lo_u32 v3, v1, v2
	v_sub_u32_e32 v3, v5, v3
	v_add_u32_e32 v4, 1, v1
	v_cmp_ge_u32_e32 vcc, v3, v2
	s_nop 1
	v_cndmask_b32_e32 v1, v1, v4, vcc
	v_sub_u32_e32 v4, v3, v2
	v_cndmask_b32_e32 v3, v3, v4, vcc
	v_add_u32_e32 v4, 1, v1
	v_cmp_ge_u32_e32 vcc, v3, v2
	v_add_u32_e32 v3, 1, v5
	s_nop 0
	v_cndmask_b32_e32 v1, v1, v4, vcc
	v_mul_lo_u32 v4, v2, v1
	v_add_u32_e32 v2, v4, v2
	v_cmp_ne_u32_e32 vcc, v3, v2
	s_and_saveexec_b64 s[10:11], vcc
	s_xor_b64 s[10:11], exec, s[10:11]
	s_cbranch_execz .LBB0_705
	s_waitcnt lgkmcnt(0)
	buffer_inv sc1
	v_mov_b32_e32 v0, 0x2000
	global_load_dword v0, v0, s[6:7] offset:1024 sc1
	s_add_u32 s16, s6, 0x2400
	s_addc_u32 s17, s7, 0
	s_waitcnt vmcnt(0)
	v_cmp_le_u32_e32 vcc, v0, v1
	s_and_saveexec_b64 s[12:13], vcc
	s_cbranch_execz .LBB0_704
	s_add_u32 s14, s58, 0xc0200
	s_addc_u32 s15, s59, 0
	s_mov_b32 s3, 1
	s_mov_b64 s[18:19], 0
	v_mov_b32_e32 v0, 0
	s_branch .LBB0_695

; __device__ __forceinline__ unsigned xb_ld(unsigned* p)              { return __hip_atomic_load(p, __ATOMIC_RELAXED, __HIP_MEMORY_SCOPE_AGENT); }
; #define XB_SPIN(cond, bar) do { unsigned _sp = 0; while (cond) { __builtin_amdgcn_s_sleep(1); \
;     if ((++_sp & 255u) == 0u) { if (xb_ld(&(bar)[XB_TMO])) break; if (_sp > XB_SPIN_CAP) { atomicAdd(&(bar)[XB_TMO], 1u); break; } } } } while (0)
; __device__ __forceinline__ void xcd_barrier(const XcdBarrier& b) {
;     ...
;             XB_SPIN(xb_ld(&bar[XB_XGEN(b.x)]) == gen, bar);
.LBB0_699:
	global_load_dword v2, v0, s[16:17] sc1
	s_add_i32 s3, s3, 1
	s_mov_b64 s[24:25], -1
	s_waitcnt vmcnt(0)
	v_cmp_gt_u32_e32 vcc, v2, v1
	s_orn2_b64 s[22:23], vcc, exec
	s_branch .LBB0_694

; __device__ __forceinline__ unsigned xb_ld(unsigned* p)              { return __hip_atomic_load(p, __ATOMIC_RELAXED, __HIP_MEMORY_SCOPE_AGENT); }
; __device__ __forceinline__ unsigned xb_add(unsigned* p, unsigned v) { return __hip_atomic_fetch_add(p, v, __ATOMIC_RELAXED, __HIP_MEMORY_SCOPE_AGENT); }
; #define XB_SPIN(cond, bar) do { unsigned _sp = 0; while (cond) { __builtin_amdgcn_s_sleep(1); \
;     if ((++_sp & 255u) == 0u) { if (xb_ld(&(bar)[XB_TMO])) break; if (_sp > XB_SPIN_CAP) { atomicAdd(&(bar)[XB_TMO], 1u); break; } } } } while (0)
; __device__ __forceinline__ void xcd_barrier(const XcdBarrier& b) {
;     ...
;             const unsigned og = xb_add(&bar[XB_TOP], 1u);
;             const unsigned tg = og / nx;
;             if (og + 1u == (tg + 1u) * nx) xb_add(&bar[XB_TOPGEN], 1u);
;             else XB_SPIN(xb_ld(&bar[XB_TOPGEN]) == tg, bar);
.LBB0_708:
	s_or_b64 exec, exec, s[12:13]
	v_cvt_f32_u32_e32 v3, v0
	s_waitcnt vmcnt(0)
	v_readfirstlane_b32 s3, v2
	s_add_u32 s12, s58, 0xc3500
	s_addc_u32 s13, s59, 0
	v_rcp_iflag_f32_e32 v3, v3
	v_add_u32_e32 v1, s3, v1
	v_add_u32_e32 v4, 1, v1
	s_mov_b64 s[14:15], -1
	v_mul_f32_e32 v2, 0x4f7ffffe, v3
	v_cvt_u32_f32_e32 v2, v2
	v_sub_u32_e32 v3, 0, v0
	v_mul_lo_u32 v3, v3, v2
	v_mul_hi_u32 v3, v2, v3
	v_add_u32_e32 v2, v2, v3
	v_mul_hi_u32 v2, v1, v2
	v_mul_lo_u32 v3, v2, v0
	v_sub_u32_e32 v1, v1, v3
	v_add_u32_e32 v5, 1, v2
	v_cmp_ge_u32_e32 vcc, v1, v0
	v_sub_u32_e32 v3, v1, v0
	s_nop 0
	v_cndmask_b32_e32 v2, v2, v5, vcc
	v_cndmask_b32_e32 v1, v1, v3, vcc
	v_add_u32_e32 v3, 1, v2
	v_cmp_ge_u32_e32 vcc, v1, v0
	s_nop 1
	v_cndmask_b32_e32 v2, v2, v3, vcc
	v_mul_lo_u32 v1, v0, v2
	v_add_u32_e32 v0, v1, v0
	v_cmp_ne_u32_e32 vcc, v4, v0
	v_mov_b32_e32 v2, v0
	v_mov_b64_e32 v[0:1], s[12:13]
	s_and_saveexec_b64 s[10:11], vcc
	s_cbranch_execz .LBB0_720
	s_sub_u32 s12, s12, 0x100
	s_subb_u32 s13, s13, 0
	v_mov_b32_e32 v0, 0
	global_load_dword v1, v0, s[12:13] sc1
	s_mov_b64 s[18:19], 0
	s_waitcnt vmcnt(0)
	v_cmp_lt_u32_e32 vcc, v1, v2
	s_and_saveexec_b64 s[16:17], vcc
	s_cbranch_execz .LBB0_719
	s_add_u32 s14, s58, 0xc0200
	s_addc_u32 s15, s59, 0
	s_mov_b32 s3, 1
	s_branch .LBB0_712

; __device__ __forceinline__ unsigned xb_ld(unsigned* p)              { return __hip_atomic_load(p, __ATOMIC_RELAXED, __HIP_MEMORY_SCOPE_AGENT); }
; #define XB_SPIN(cond, bar) do { unsigned _sp = 0; while (cond) { __builtin_amdgcn_s_sleep(1); \
;     if ((++_sp & 255u) == 0u) { if (xb_ld(&(bar)[XB_TMO])) break; if (_sp > XB_SPIN_CAP) { atomicAdd(&(bar)[XB_TMO], 1u); break; } } } } while (0)
; __device__ __forceinline__ void xcd_barrier(const XcdBarrier& b) {
;     ...
;             else XB_SPIN(xb_ld(&bar[XB_TOPGEN]) == tg, bar);
.LBB0_716:
	global_load_dword v1, v0, s[12:13] sc1
	s_add_i32 s3, s3, 1
	s_mov_b64 s[22:23], -1
	s_waitcnt vmcnt(0)
	v_cmp_ge_u32_e32 vcc, v1, v2
	s_orn2_b64 s[26:27], vcc, exec
	s_branch .LBB0_711
